# v85 + lora2 item set-up loads as a 17-deep rolling window
# speedup vs baseline: 1.0034x; 1.0017x over previous
.LBB0_453:
	s_sub_i32 s2, s54, s56
	s_lshr_b32 s2, s2, 3
	s_add_i32 s2, s2, s56
	s_cmp_lt_i32 s54, s56
	s_cselect_b32 s24, s54, s2
	s_cselect_b32 s10, 0, s58
	s_cselect_b32 s60, 8, s59
	s_lshl_b32 s2, s24, 3
	v_and_or_b32 v56, s2, -16, v226
	v_cmp_gt_i32_e32 vcc, s71, v56
	v_mov_b32_e32 v0, 0xff
	v_mov_b32_e32 v1, 0x1fff
	v_cndmask_b32_e32 v0, v0, v1, vcc
	v_and_b32_e32 v1, v0, v56
	v_cmp_eq_u32_e64 s[38:39], 0, v1
	v_cmp_eq_u32_e64 s[36:37], v1, v0
	v_mul_u32_u24_e32 v236, 0x2e00, v56
	v_mbcnt_lo_u32_b32 v214, -1, 0
	v_mbcnt_hi_u32_b32 v214, -1, v214
	v_and_b32_e32 v214, 48, v214
	v_add_u32_e32 v214, 0x21402a00, v214
	v_add_u32_e32 v236, v236, v214
	v_mov_b32_e32 v215, 0x2e00
	v_cndmask_b32_e64 v214, v215, 0, s[38:39]
	v_sub_u32_e32 v237, v236, v214
	v_cndmask_b32_e64 v214, v215, 0, s[36:37]
	v_add_u32_e32 v238, v236, v214
	global_load_dwordx4 v[116:119], v236, s[74:75]
	global_load_dwordx4 v[120:123], v237, s[74:75]
	global_load_dwordx4 v[124:127], v[172:173], off offset:16
	global_load_dwordx4 v[128:131], v[172:173], off
	global_load_dwordx4 v[132:135], v236, s[74:75] offset:256
	global_load_dwordx4 v[136:139], v237, s[74:75] offset:256
	global_load_dwordx4 v[140:143], v[174:175], off offset:16
	global_load_dwordx4 v[144:147], v[174:175], off
	global_load_dwordx4 v[148:151], v236, s[74:75] offset:64
	global_load_dwordx4 v[152:155], v237, s[74:75] offset:64
	global_load_dwordx4 v[156:159], v[172:173], off offset:144
	global_load_dwordx4 v[160:163], v[172:173], off offset:128
	global_load_dwordx4 v[210:213], v236, s[74:75] offset:320
	global_load_dwordx4 v[232:235], v237, s[74:75] offset:320
	global_load_dwordx4 v[240:243], v[174:175], off offset:144
	global_load_dwordx4 v[244:247], v[174:175], off offset:128
	global_load_dwordx4 v[248:251], v236, s[74:75] offset:128
	v_mov_b64_e32 v[0:1], s[40:41]
	v_mad_i64_i32 v[0:1], s[4:5], v56, s17, v[0:1]
	v_mov_b32_e32 v2, 0xffffd200
	v_cndmask_b32_e64 v3, -1, 0, s[38:39]
	v_cndmask_b32_e64 v2, v2, 0, s[38:39]
	v_lshl_add_u64 v[34:35], v[0:1], 0, v[166:167]
	v_lshl_add_u64 v[8:9], v[0:1], 0, v[2:3]
	v_mov_b32_e32 v2, 0x2e00
	v_add_co_u32_e32 v36, vcc, s79, v34
	v_cndmask_b32_e64 v208, v2, 0, s[36:37]
	s_nop 0
	v_addc_co_u32_e32 v37, vcc, 0, v35, vcc
	v_lshl_add_u64 v[32:33], v[0:1], 0, v[208:209]
	s_waitcnt vmcnt(16)
	v_mov_b32_e32 v0, v116
	v_mov_b32_e32 v1, v117
	v_mov_b32_e32 v2, v118
	v_mov_b32_e32 v3, v119
	global_load_dwordx4 v[116:119], v238, s[74:75] offset:128
	v_lshl_add_u64 v[40:41], v[8:9], 0, v[166:167]
	v_add_co_u32_e32 v38, vcc, s79, v40
	s_mov_b64 s[8:9], 0x2a00
	s_nop 0
	v_addc_co_u32_e32 v39, vcc, 0, v41, vcc
	v_lshl_add_u64 v[24:25], v[34:35], 0, s[8:9]
	v_lshl_add_u64 v[8:9], v[40:41], 0, s[8:9]
	s_mov_b64 s[12:13], 0x2b00
	v_lshl_add_u64 v[28:29], v[34:35], 0, s[12:13]
	s_lshl_b32 s2, s24, 9
	s_and_b32 s2, s2, 0x200
	v_ashrrev_i32_e32 v57, 31, v56
	v_mov_b32_e32 v197, v209
	v_lshlrev_b32_e32 v18, 16, v0
	v_and_b32_e32 v19, 0xffff0000, v0
	v_lshlrev_b32_e32 v20, 16, v1
	v_and_b32_e32 v21, 0xffff0000, v1
	v_lshlrev_b32_e32 v4, 16, v2
	v_and_b32_e32 v5, 0xffff0000, v2
	v_lshlrev_b32_e32 v6, 16, v3
	v_and_b32_e32 v7, 0xffff0000, v3
	s_waitcnt vmcnt(16)
	v_mov_b32_e32 v0, v120
	v_mov_b32_e32 v1, v121
	v_mov_b32_e32 v2, v122
	v_mov_b32_e32 v3, v123
	global_load_dwordx4 v[120:123], v[172:173], off offset:272
	v_cndmask_b32_e64 v3, v3, 0, s[38:39]
	v_cndmask_b32_e64 v2, v2, 0, s[38:39]
	v_cndmask_b32_e64 v1, v1, 0, s[38:39]
	v_cndmask_b32_e64 v0, v0, 0, s[38:39]
	v_lshlrev_b32_e32 v22, 16, v0
	v_and_b32_e32 v23, 0xffff0000, v0
	v_lshlrev_b32_e32 v26, 16, v1
	v_and_b32_e32 v27, 0xffff0000, v1
	v_lshlrev_b32_e32 v14, 16, v2
	v_and_b32_e32 v16, 0xffff0000, v2
	v_lshlrev_b32_e32 v15, 16, v3
	v_and_b32_e32 v17, 0xffff0000, v3
	s_waitcnt vmcnt(16)
	v_mov_b32_e32 v0, v124
	v_mov_b32_e32 v1, v125
	v_mov_b32_e32 v2, v126
	v_mov_b32_e32 v3, v127
	global_load_dwordx4 v[124:127], v[172:173], off offset:256
	s_waitcnt vmcnt(16)
	v_mov_b32_e32 v10, v128
	v_mov_b32_e32 v11, v129
	v_mov_b32_e32 v12, v130
	v_mov_b32_e32 v13, v131
	global_load_dwordx4 v[128:131], v236, s[74:75] offset:384
	v_sub_f32_e32 v23, v23, v19
	v_sub_f32_e32 v22, v22, v18
	v_sub_f32_e32 v27, v27, v21
	v_sub_f32_e32 v26, v26, v20
	v_sub_f32_e32 v17, v17, v7
	v_pk_fma_f32 v[10:11], v[10:11], v[22:23], v[18:19]
	s_nop 0
	v_add_f32_e32 v10, v10, v10
	v_add_f32_e32 v11, v11, v11
	v_mul_f32_e32 v10, 0x3fb8aa3b, v10
	v_mul_f32_e32 v11, 0x3fb8aa3b, v11
	v_exp_f32_e32 v10, v10
	v_exp_f32_e32 v11, v11
	v_pk_fma_f32 v[12:13], v[12:13], v[26:27], v[20:21]
	v_pk_add_f32 v[10:11], v[10:11], 1.0 op_sel_hi:[1,0]
	s_nop 0
	v_div_scale_f32 v18, s[4:5], v11, v11, 2.0
	v_rcp_f32_e32 v19, v18
	v_add_f32_e32 v12, v12, v12
	v_add_f32_e32 v13, v13, v13
	v_mul_f32_e32 v12, 0x3fb8aa3b, v12
	v_fma_f32 v20, -v18, v19, 1.0
	v_fmac_f32_e32 v19, v20, v19
	v_div_scale_f32 v20, vcc, 2.0, v11, 2.0
	v_mul_f32_e32 v21, v20, v19
	v_fma_f32 v22, -v18, v21, v20
	v_fmac_f32_e32 v21, v22, v19
	v_fma_f32 v18, -v18, v21, v20
	v_div_fmas_f32 v18, v18, v19, v21
	v_div_fixup_f32 v11, v18, v11, 2.0
	v_div_scale_f32 v18, s[4:5], v10, v10, 2.0
	v_rcp_f32_e32 v19, v18
	v_mul_f32_e32 v13, 0x3fb8aa3b, v13
	v_exp_f32_e32 v12, v12
	v_exp_f32_e32 v13, v13
	v_fma_f32 v20, -v18, v19, 1.0
	v_fmac_f32_e32 v19, v20, v19
	v_div_scale_f32 v20, vcc, 2.0, v10, 2.0
	v_mul_f32_e32 v21, v20, v19
	v_fma_f32 v22, -v18, v21, v20
	v_fmac_f32_e32 v21, v22, v19
	v_fma_f32 v18, -v18, v21, v20
	v_div_fmas_f32 v18, v18, v19, v21
	v_pk_add_f32 v[12:13], v[12:13], 1.0 op_sel_hi:[1,0]
	v_div_fixup_f32 v10, v18, v10, 2.0
	v_div_scale_f32 v18, s[4:5], v13, v13, 2.0
	v_rcp_f32_e32 v19, v18
	v_pk_add_f32 v[10:11], v[10:11], 1.0 op_sel_hi:[1,0] neg_lo:[1,0] neg_hi:[1,0]
	v_fma_f32 v20, -v18, v19, 1.0
	v_fmac_f32_e32 v19, v20, v19
	v_div_scale_f32 v20, vcc, 2.0, v13, 2.0
	v_mul_f32_e32 v21, v20, v19
	v_fma_f32 v22, -v18, v21, v20
	v_fmac_f32_e32 v21, v22, v19
	v_fma_f32 v18, -v18, v21, v20
	v_div_fmas_f32 v18, v18, v19, v21
	v_div_fixup_f32 v13, v18, v13, 2.0
	v_div_scale_f32 v18, s[4:5], v12, v12, 2.0
	v_rcp_f32_e32 v19, v18
	s_nop 0
	v_fma_f32 v20, -v18, v19, 1.0
	v_fmac_f32_e32 v19, v20, v19
	v_div_scale_f32 v20, vcc, 2.0, v12, 2.0
	v_mul_f32_e32 v21, v20, v19
	v_fma_f32 v22, -v18, v21, v20
	v_fmac_f32_e32 v21, v22, v19
	v_fma_f32 v18, -v18, v21, v20
	v_div_fmas_f32 v18, v18, v19, v21
	v_div_fixup_f32 v12, v18, v12, 2.0
	v_sub_f32_e32 v19, v16, v5
	v_sub_f32_e32 v18, v14, v4
	v_pk_fma_f32 v[0:1], v[0:1], v[18:19], v[4:5]
	v_sub_f32_e32 v16, v15, v6
	v_add_f32_e32 v0, v0, v0
	v_add_f32_e32 v1, v1, v1
	v_mul_f32_e32 v0, 0x3fb8aa3b, v0
	v_mul_f32_e32 v1, 0x3fb8aa3b, v1
	v_exp_f32_e32 v0, v0
	v_exp_f32_e32 v1, v1
	v_pk_fma_f32 v[2:3], v[2:3], v[16:17], v[6:7]
	v_pk_add_f32 v[12:13], v[12:13], 1.0 op_sel_hi:[1,0] neg_lo:[1,0] neg_hi:[1,0]
	v_pk_add_f32 v[0:1], v[0:1], 1.0 op_sel_hi:[1,0]
	s_nop 0
	v_div_scale_f32 v4, s[4:5], v1, v1, 2.0
	v_rcp_f32_e32 v5, v4
	s_nop 0
	v_fma_f32 v6, -v4, v5, 1.0
	v_fmac_f32_e32 v5, v6, v5
	v_div_scale_f32 v6, vcc, 2.0, v1, 2.0
	v_mul_f32_e32 v7, v6, v5
	v_fma_f32 v14, -v4, v7, v6
	v_fmac_f32_e32 v7, v14, v5
	v_fma_f32 v4, -v4, v7, v6
	v_div_fmas_f32 v4, v4, v5, v7
	v_div_fixup_f32 v1, v4, v1, 2.0
	v_div_scale_f32 v4, s[4:5], v0, v0, 2.0
	v_rcp_f32_e32 v5, v4
	s_nop 0
	v_fma_f32 v6, -v4, v5, 1.0
	v_fmac_f32_e32 v5, v6, v5
	v_div_scale_f32 v6, vcc, 2.0, v0, 2.0
	v_mul_f32_e32 v7, v6, v5
	v_fma_f32 v14, -v4, v7, v6
	v_fmac_f32_e32 v7, v14, v5
	v_fma_f32 v4, -v4, v7, v6
	v_div_fmas_f32 v4, v4, v5, v7
	v_div_fixup_f32 v0, v4, v0, 2.0
	v_pk_add_f32 v[4:5], v[0:1], 1.0 op_sel_hi:[1,0] neg_lo:[1,0] neg_hi:[1,0]
	v_add_f32_e32 v0, v2, v2
	v_add_f32_e32 v1, v3, v3
	v_mul_f32_e32 v0, 0x3fb8aa3b, v0
	v_mul_f32_e32 v1, 0x3fb8aa3b, v1
	v_exp_f32_e32 v0, v0
	v_exp_f32_e32 v1, v1
	s_nop 0
	v_pk_add_f32 v[0:1], v[0:1], 1.0 op_sel_hi:[1,0]
	s_nop 0
	v_div_scale_f32 v2, s[4:5], v1, v1, 2.0
	v_rcp_f32_e32 v3, v2
	s_nop 0
	v_fma_f32 v6, -v2, v3, 1.0
	v_fmac_f32_e32 v3, v6, v3
	v_div_scale_f32 v6, vcc, 2.0, v1, 2.0
	v_mul_f32_e32 v7, v6, v3
	v_fma_f32 v14, -v2, v7, v6
	v_fmac_f32_e32 v7, v14, v3
	v_fma_f32 v2, -v2, v7, v6
	v_div_fmas_f32 v2, v2, v3, v7
	v_div_fixup_f32 v1, v2, v1, 2.0
	v_div_scale_f32 v2, s[4:5], v0, v0, 2.0
	v_rcp_f32_e32 v3, v2
	s_nop 0
	v_fma_f32 v6, -v2, v3, 1.0
	v_fmac_f32_e32 v3, v6, v3
	v_div_scale_f32 v6, vcc, 2.0, v0, 2.0
	v_mul_f32_e32 v7, v6, v3
	v_fma_f32 v14, -v2, v7, v6
	v_fmac_f32_e32 v7, v14, v3
	v_fma_f32 v2, -v2, v7, v6
	v_div_fmas_f32 v2, v2, v3, v7
	v_div_fixup_f32 v0, v2, v0, 2.0
	v_pk_add_f32 v[6:7], v[0:1], 1.0 op_sel_hi:[1,0] neg_lo:[1,0] neg_hi:[1,0]
	v_cvt_pk_bf16_f32 v0, v10, v11
	v_cvt_pk_bf16_f32 v1, v12, v13
	v_cvt_pk_bf16_f32 v2, v4, v5
	v_cvt_pk_bf16_f32 v3, v6, v7
	s_waitcnt vmcnt(16)
	v_mov_b32_e32 v4, v132
	v_mov_b32_e32 v5, v133
	v_mov_b32_e32 v6, v134
	v_mov_b32_e32 v7, v135
	global_load_dwordx4 v[132:135], v238, s[74:75] offset:384
	v_lshl_add_u64 v[12:13], v[40:41], 0, s[12:13]
	v_lshlrev_b32_e32 v10, 16, v4
	v_and_b32_e32 v11, 0xffff0000, v4
	v_lshlrev_b32_e32 v18, 16, v5
	v_and_b32_e32 v19, 0xffff0000, v5
	v_lshlrev_b32_e32 v20, 16, v6
	v_and_b32_e32 v21, 0xffff0000, v6
	v_lshlrev_b32_e32 v22, 16, v7
	v_and_b32_e32 v23, 0xffff0000, v7
	s_waitcnt vmcnt(16)
	v_mov_b32_e32 v4, v136
	v_mov_b32_e32 v5, v137
	v_mov_b32_e32 v6, v138
	v_mov_b32_e32 v7, v139
	global_load_dwordx4 v[136:139], v[174:175], off offset:272
	v_cndmask_b32_e64 v7, v7, 0, s[38:39]
	v_cndmask_b32_e64 v6, v6, 0, s[38:39]
	v_cndmask_b32_e64 v5, v5, 0, s[38:39]
	v_cndmask_b32_e64 v4, v4, 0, s[38:39]
	v_lshlrev_b32_e32 v26, 16, v4
	v_and_b32_e32 v27, 0xffff0000, v4
	v_lshlrev_b32_e32 v30, 16, v5
	v_and_b32_e32 v31, 0xffff0000, v5
	v_lshlrev_b32_e32 v42, 16, v6
	v_and_b32_e32 v43, 0xffff0000, v6
	v_lshlrev_b32_e32 v44, 16, v7
	v_and_b32_e32 v45, 0xffff0000, v7
	s_waitcnt vmcnt(16)
	v_mov_b32_e32 v4, v140
	v_mov_b32_e32 v5, v141
	v_mov_b32_e32 v6, v142
	v_mov_b32_e32 v7, v143
	global_load_dwordx4 v[140:143], v[174:175], off offset:256
	s_waitcnt vmcnt(16)
	v_mov_b32_e32 v14, v144
	v_mov_b32_e32 v15, v145
	v_mov_b32_e32 v16, v146
	v_mov_b32_e32 v17, v147
	global_load_dwordx4 v[144:147], v236, s[74:75] offset:192
	v_sub_f32_e32 v27, v27, v11
	v_sub_f32_e32 v26, v26, v10
	v_sub_f32_e32 v31, v31, v19
	v_sub_f32_e32 v30, v30, v18
	v_pk_fma_f32 v[16:17], v[16:17], v[30:31], v[18:19]
	v_pk_fma_f32 v[10:11], v[14:15], v[26:27], v[10:11]
	v_sub_f32_e32 v15, v43, v21
	v_sub_f32_e32 v14, v42, v20
	v_sub_f32_e32 v19, v45, v23
	v_sub_f32_e32 v18, v44, v22
	v_pk_fma_f32 v[18:19], v[6:7], v[18:19], v[22:23]
	v_pk_fma_f32 v[6:7], v[4:5], v[14:15], v[20:21]
	v_cvt_pk_bf16_f32 v4, v10, v11
	v_cvt_pk_bf16_f32 v5, v16, v17
	v_cvt_pk_bf16_f32 v6, v6, v7
	v_cvt_pk_bf16_f32 v7, v18, v19
	s_waitcnt vmcnt(16)
	v_mov_b32_e32 v14, v148
	v_mov_b32_e32 v15, v149
	v_mov_b32_e32 v16, v150
	v_mov_b32_e32 v17, v151
	global_load_dwordx4 v[148:151], v238, s[74:75] offset:192
	s_nop 0
	s_waitcnt vmcnt(16)
	v_mov_b32_e32 v8, v152
	v_mov_b32_e32 v9, v153
	v_mov_b32_e32 v10, v154
	v_mov_b32_e32 v11, v155
	global_load_dwordx4 v[152:155], v[172:173], off offset:400
	v_lshlrev_b32_e32 v26, 16, v14
	v_and_b32_e32 v27, 0xffff0000, v14
	v_cndmask_b32_e64 v11, v11, 0, s[38:39]
	v_cndmask_b32_e64 v10, v10, 0, s[38:39]
	v_cndmask_b32_e64 v9, v9, 0, s[38:39]
	v_cndmask_b32_e64 v8, v8, 0, s[38:39]
	v_lshlrev_b32_e32 v42, 16, v8
	v_and_b32_e32 v43, 0xffff0000, v8
	v_lshlrev_b32_e32 v44, 16, v9
	v_and_b32_e32 v45, 0xffff0000, v9
	v_lshlrev_b32_e32 v22, 16, v10
	v_and_b32_e32 v46, 0xffff0000, v10
	v_lshlrev_b32_e32 v23, 16, v11
	v_and_b32_e32 v47, 0xffff0000, v11
	s_waitcnt vmcnt(16)
	v_mov_b32_e32 v8, v156
	v_mov_b32_e32 v9, v157
	v_mov_b32_e32 v10, v158
	v_mov_b32_e32 v11, v159
	global_load_dwordx4 v[156:159], v[172:173], off offset:384
	s_waitcnt vmcnt(16)
	v_mov_b32_e32 v18, v160
	v_mov_b32_e32 v19, v161
	v_mov_b32_e32 v20, v162
	v_mov_b32_e32 v21, v163
	global_load_dwordx4 v[160:163], v236, s[74:75] offset:448
	v_sub_f32_e32 v43, v43, v27
	v_sub_f32_e32 v42, v42, v26
	v_lshlrev_b32_e32 v30, 16, v15
	v_and_b32_e32 v31, 0xffff0000, v15
	v_sub_f32_e32 v45, v45, v31
	v_sub_f32_e32 v44, v44, v30
	v_lshlrev_b32_e32 v14, 16, v16
	v_and_b32_e32 v15, 0xffff0000, v16
	v_lshlrev_b32_e32 v16, 16, v17
	v_and_b32_e32 v17, 0xffff0000, v17
	v_pk_fma_f32 v[18:19], v[18:19], v[42:43], v[26:27]
	s_nop 0
	v_add_f32_e32 v18, v18, v18
	v_add_f32_e32 v19, v19, v19
	v_mul_f32_e32 v18, 0x3fb8aa3b, v18
	v_mul_f32_e32 v19, 0x3fb8aa3b, v19
	v_exp_f32_e32 v18, v18
	v_exp_f32_e32 v19, v19
	v_pk_fma_f32 v[20:21], v[20:21], v[44:45], v[30:31]
	v_pk_add_f32 v[18:19], v[18:19], 1.0 op_sel_hi:[1,0]
	s_nop 0
	v_div_scale_f32 v26, s[4:5], v19, v19, 2.0
	v_rcp_f32_e32 v27, v26
	v_add_f32_e32 v20, v20, v20
	v_add_f32_e32 v21, v21, v21
	v_mul_f32_e32 v20, 0x3fb8aa3b, v20
	v_fma_f32 v30, -v26, v27, 1.0
	v_fmac_f32_e32 v27, v30, v27
	v_div_scale_f32 v30, vcc, 2.0, v19, 2.0
	v_mul_f32_e32 v31, v30, v27
	v_fma_f32 v42, -v26, v31, v30
	v_fmac_f32_e32 v31, v42, v27
	v_fma_f32 v26, -v26, v31, v30
	v_div_fmas_f32 v26, v26, v27, v31
	v_div_fixup_f32 v19, v26, v19, 2.0
	v_div_scale_f32 v26, s[4:5], v18, v18, 2.0
	v_rcp_f32_e32 v27, v26
	v_mul_f32_e32 v21, 0x3fb8aa3b, v21
	v_exp_f32_e32 v20, v20
	v_exp_f32_e32 v21, v21
	v_fma_f32 v30, -v26, v27, 1.0
	v_fmac_f32_e32 v27, v30, v27
	v_div_scale_f32 v30, vcc, 2.0, v18, 2.0
	v_mul_f32_e32 v31, v30, v27
	v_fma_f32 v42, -v26, v31, v30
	v_fmac_f32_e32 v31, v42, v27
	v_fma_f32 v26, -v26, v31, v30
	v_div_fmas_f32 v26, v26, v27, v31
	v_pk_add_f32 v[20:21], v[20:21], 1.0 op_sel_hi:[1,0]
	v_div_fixup_f32 v18, v26, v18, 2.0
	v_div_scale_f32 v26, s[4:5], v21, v21, 2.0
	v_rcp_f32_e32 v27, v26
	v_pk_add_f32 v[18:19], v[18:19], 1.0 op_sel_hi:[1,0] neg_lo:[1,0] neg_hi:[1,0]
	v_fma_f32 v30, -v26, v27, 1.0
	v_fmac_f32_e32 v27, v30, v27
	v_div_scale_f32 v30, vcc, 2.0, v21, 2.0
	v_mul_f32_e32 v31, v30, v27
	v_fma_f32 v42, -v26, v31, v30
	v_fmac_f32_e32 v31, v42, v27
	v_fma_f32 v26, -v26, v31, v30
	v_div_fmas_f32 v26, v26, v27, v31
	v_div_fixup_f32 v21, v26, v21, 2.0
	v_div_scale_f32 v26, s[4:5], v20, v20, 2.0
	v_rcp_f32_e32 v27, v26
	s_nop 0
	v_fma_f32 v30, -v26, v27, 1.0
	v_fmac_f32_e32 v27, v30, v27
	v_div_scale_f32 v30, vcc, 2.0, v20, 2.0
	v_mul_f32_e32 v31, v30, v27
	v_fma_f32 v42, -v26, v31, v30
	v_fmac_f32_e32 v31, v42, v27
	v_fma_f32 v26, -v26, v31, v30
	v_div_fmas_f32 v26, v26, v27, v31
	v_div_fixup_f32 v20, v26, v20, 2.0
	v_sub_f32_e32 v27, v46, v15
	v_sub_f32_e32 v26, v22, v14
	v_pk_fma_f32 v[8:9], v[8:9], v[26:27], v[14:15]
	v_sub_f32_e32 v31, v47, v17
	v_add_f32_e32 v8, v8, v8
	v_add_f32_e32 v9, v9, v9
	v_mul_f32_e32 v8, 0x3fb8aa3b, v8
	v_mul_f32_e32 v9, 0x3fb8aa3b, v9
	v_exp_f32_e32 v8, v8
	v_exp_f32_e32 v9, v9
	v_sub_f32_e32 v30, v23, v16
	v_pk_fma_f32 v[10:11], v[10:11], v[30:31], v[16:17]
	v_pk_add_f32 v[20:21], v[20:21], 1.0 op_sel_hi:[1,0] neg_lo:[1,0] neg_hi:[1,0]
	v_pk_add_f32 v[8:9], v[8:9], 1.0 op_sel_hi:[1,0]
	s_nop 0
	v_div_scale_f32 v14, s[4:5], v9, v9, 2.0
	v_rcp_f32_e32 v15, v14
	s_nop 0
	v_fma_f32 v16, -v14, v15, 1.0
	v_fmac_f32_e32 v15, v16, v15
	v_div_scale_f32 v16, vcc, 2.0, v9, 2.0
	v_mul_f32_e32 v17, v16, v15
	v_fma_f32 v22, -v14, v17, v16
	v_fmac_f32_e32 v17, v22, v15
	v_fma_f32 v14, -v14, v17, v16
	v_div_fmas_f32 v14, v14, v15, v17
	v_div_fixup_f32 v9, v14, v9, 2.0
	v_div_scale_f32 v14, s[4:5], v8, v8, 2.0
	v_rcp_f32_e32 v15, v14
	s_nop 0
	v_fma_f32 v16, -v14, v15, 1.0
	v_fmac_f32_e32 v15, v16, v15
	v_div_scale_f32 v16, vcc, 2.0, v8, 2.0
	v_mul_f32_e32 v17, v16, v15
	v_fma_f32 v22, -v14, v17, v16
	v_fmac_f32_e32 v17, v22, v15
	v_fma_f32 v14, -v14, v17, v16
	v_div_fmas_f32 v14, v14, v15, v17
	v_div_fixup_f32 v8, v14, v8, 2.0
	v_pk_add_f32 v[14:15], v[8:9], 1.0 op_sel_hi:[1,0] neg_lo:[1,0] neg_hi:[1,0]
	v_add_f32_e32 v8, v10, v10
	v_add_f32_e32 v9, v11, v11
	v_mul_f32_e32 v8, 0x3fb8aa3b, v8
	v_mul_f32_e32 v9, 0x3fb8aa3b, v9
	v_exp_f32_e32 v8, v8
	v_exp_f32_e32 v9, v9
	s_nop 0
	v_pk_add_f32 v[8:9], v[8:9], 1.0 op_sel_hi:[1,0]
	s_nop 0
	v_div_scale_f32 v10, s[4:5], v9, v9, 2.0
	v_rcp_f32_e32 v11, v10
	s_nop 0
	v_fma_f32 v16, -v10, v11, 1.0
	v_fmac_f32_e32 v11, v16, v11
	v_div_scale_f32 v16, vcc, 2.0, v9, 2.0
	v_mul_f32_e32 v17, v16, v11
	v_fma_f32 v22, -v10, v17, v16
	v_fmac_f32_e32 v17, v22, v11
	v_fma_f32 v10, -v10, v17, v16
	v_div_fmas_f32 v10, v10, v11, v17
	v_div_fixup_f32 v9, v10, v9, 2.0
	v_div_scale_f32 v10, s[4:5], v8, v8, 2.0
	v_rcp_f32_e32 v11, v10
	s_nop 0
	v_fma_f32 v16, -v10, v11, 1.0
	v_fmac_f32_e32 v11, v16, v11
	v_div_scale_f32 v16, vcc, 2.0, v8, 2.0
	v_mul_f32_e32 v17, v16, v11
	v_fma_f32 v22, -v10, v17, v16
	v_fmac_f32_e32 v17, v22, v11
	v_fma_f32 v10, -v10, v17, v16
	v_div_fmas_f32 v10, v10, v11, v17
	v_div_fixup_f32 v8, v10, v8, 2.0
	v_pk_add_f32 v[16:17], v[8:9], 1.0 op_sel_hi:[1,0] neg_lo:[1,0] neg_hi:[1,0]
	v_cvt_pk_bf16_f32 v8, v18, v19
	v_cvt_pk_bf16_f32 v9, v20, v21
	v_cvt_pk_bf16_f32 v10, v14, v15
	v_cvt_pk_bf16_f32 v11, v16, v17
	s_waitcnt vmcnt(16)
	v_mov_b32_e32 v14, v210
	v_mov_b32_e32 v15, v211
	v_mov_b32_e32 v16, v212
	v_mov_b32_e32 v17, v213
	global_load_dwordx4 v[210:213], v238, s[74:75] offset:448
	v_lshlrev_b32_e32 v20, 16, v14
	v_and_b32_e32 v21, 0xffff0000, v14
	v_lshlrev_b32_e32 v22, 16, v15
	v_and_b32_e32 v23, 0xffff0000, v15
	s_waitcnt vmcnt(16)
	v_mov_b32_e32 v12, v232
	v_mov_b32_e32 v13, v233
	v_mov_b32_e32 v14, v234
	v_mov_b32_e32 v15, v235
	global_load_dwordx4 v[232:235], v[174:175], off offset:400
	v_lshlrev_b32_e32 v26, 16, v16
	v_and_b32_e32 v27, 0xffff0000, v16
	v_lshlrev_b32_e32 v30, 16, v17
	v_and_b32_e32 v31, 0xffff0000, v17
	v_cndmask_b32_e64 v15, v15, 0, s[38:39]
	v_cndmask_b32_e64 v14, v14, 0, s[38:39]
	v_cndmask_b32_e64 v13, v13, 0, s[38:39]
	v_cndmask_b32_e64 v12, v12, 0, s[38:39]
	v_lshlrev_b32_e32 v42, 16, v12
	v_and_b32_e32 v43, 0xffff0000, v12
	v_lshlrev_b32_e32 v44, 16, v13
	v_and_b32_e32 v45, 0xffff0000, v13
	v_lshlrev_b32_e32 v46, 16, v14
	v_and_b32_e32 v47, 0xffff0000, v14
	v_lshlrev_b32_e32 v48, 16, v15
	v_and_b32_e32 v49, 0xffff0000, v15
	s_waitcnt vmcnt(16)
	v_mov_b32_e32 v12, v240
	v_mov_b32_e32 v13, v241
	v_mov_b32_e32 v14, v242
	v_mov_b32_e32 v15, v243
	global_load_dwordx4 v[240:243], v[174:175], off offset:384
	s_waitcnt vmcnt(16)
	v_mov_b32_e32 v16, v244
	v_mov_b32_e32 v17, v245
	v_mov_b32_e32 v18, v246
	v_mov_b32_e32 v19, v247
	global_load_dwordx4 v[244:247], v236, s[74:75] offset:512
	v_sub_f32_e32 v43, v43, v21
	v_sub_f32_e32 v42, v42, v20
	v_sub_f32_e32 v45, v45, v23
	v_sub_f32_e32 v44, v44, v22
	v_pk_fma_f32 v[18:19], v[18:19], v[44:45], v[22:23]
	v_pk_fma_f32 v[16:17], v[16:17], v[42:43], v[20:21]
	v_sub_f32_e32 v21, v47, v27
	v_sub_f32_e32 v20, v46, v26
	v_sub_f32_e32 v23, v49, v31
	v_sub_f32_e32 v22, v48, v30
	v_pk_fma_f32 v[22:23], v[14:15], v[22:23], v[30:31]
	v_pk_fma_f32 v[14:15], v[12:13], v[20:21], v[26:27]
	v_cvt_pk_bf16_f32 v12, v16, v17
	v_cvt_pk_bf16_f32 v13, v18, v19
	v_cvt_pk_bf16_f32 v14, v14, v15
	v_cvt_pk_bf16_f32 v15, v22, v23
	s_waitcnt vmcnt(16)
	v_mov_b32_e32 v16, v248
	v_mov_b32_e32 v17, v249
	v_mov_b32_e32 v18, v250
	v_mov_b32_e32 v19, v251
	global_load_dwordx4 v[248:251], v237, s[74:75] offset:512
	v_lshl_add_u64 v[26:27], v[32:33], 0, s[8:9]
	v_lshl_add_u64 v[30:31], v[32:33], 0, s[12:13]
	v_lshl_add_u64 v[32:33], v[32:33], 0, v[166:167]
	v_lshlrev_b32_e32 v46, 16, v16
	v_and_b32_e32 v47, 0xffff0000, v16
	v_lshlrev_b32_e32 v48, 16, v17
	v_and_b32_e32 v49, 0xffff0000, v17
	v_lshl_add_u64 v[16:17], v[26:27], 0, v[186:187]
	v_lshlrev_b32_e32 v20, 16, v18
	v_and_b32_e32 v21, 0xffff0000, v18
	v_lshlrev_b32_e32 v22, 16, v19
	v_and_b32_e32 v23, 0xffff0000, v19
	s_waitcnt vmcnt(16)
	v_mov_b32_e32 v16, v116
	v_mov_b32_e32 v17, v117
	v_mov_b32_e32 v18, v118
	v_mov_b32_e32 v19, v119
	global_load_dwordx4 v[116:119], v238, s[74:75] offset:512
	v_cndmask_b32_e64 v19, v19, 0, s[36:37]
	v_cndmask_b32_e64 v18, v18, 0, s[36:37]
	v_cndmask_b32_e64 v17, v17, 0, s[36:37]
	v_cndmask_b32_e64 v16, v16, 0, s[36:37]
	v_lshlrev_b32_e32 v50, 16, v16
	v_and_b32_e32 v51, 0xffff0000, v16
	v_lshlrev_b32_e32 v52, 16, v17
	v_and_b32_e32 v53, 0xffff0000, v17
	v_lshlrev_b32_e32 v54, 16, v18
	v_and_b32_e32 v55, 0xffff0000, v18
	v_lshlrev_b32_e32 v58, 16, v19
	v_and_b32_e32 v59, 0xffff0000, v19
	s_waitcnt vmcnt(16)
	v_mov_b32_e32 v16, v120
	v_mov_b32_e32 v17, v121
	v_mov_b32_e32 v18, v122
	v_mov_b32_e32 v19, v123
	global_load_dwordx4 v[120:123], v[176:177], off offset:16
	s_waitcnt vmcnt(16)
	v_mov_b32_e32 v42, v124
	v_mov_b32_e32 v43, v125
	v_mov_b32_e32 v44, v126
	v_mov_b32_e32 v45, v127
	global_load_dwordx4 v[124:127], v[176:177], off
	v_sub_f32_e32 v51, v51, v47
	v_sub_f32_e32 v50, v50, v46
	v_sub_f32_e32 v53, v53, v49
	v_sub_f32_e32 v52, v52, v48
	v_pk_fma_f32 v[42:43], v[42:43], v[50:51], v[46:47]
	s_nop 0
	v_add_f32_e32 v42, v42, v42
	v_add_f32_e32 v43, v43, v43
	v_mul_f32_e32 v42, 0x3fb8aa3b, v42
	v_mul_f32_e32 v43, 0x3fb8aa3b, v43
	v_exp_f32_e32 v42, v42
	v_exp_f32_e32 v43, v43
	v_pk_fma_f32 v[44:45], v[44:45], v[52:53], v[48:49]
	v_pk_add_f32 v[42:43], v[42:43], 1.0 op_sel_hi:[1,0]
	s_nop 0
	v_div_scale_f32 v46, s[4:5], v43, v43, 2.0
	v_rcp_f32_e32 v47, v46
	v_add_f32_e32 v44, v44, v44
	v_add_f32_e32 v45, v45, v45
	v_mul_f32_e32 v44, 0x3fb8aa3b, v44
	v_fma_f32 v48, -v46, v47, 1.0
	v_fmac_f32_e32 v47, v48, v47
	v_div_scale_f32 v48, vcc, 2.0, v43, 2.0
	v_mul_f32_e32 v49, v48, v47
	v_fma_f32 v50, -v46, v49, v48
	v_fmac_f32_e32 v49, v50, v47
	v_fma_f32 v46, -v46, v49, v48
	v_div_fmas_f32 v46, v46, v47, v49
	v_div_fixup_f32 v43, v46, v43, 2.0
	v_div_scale_f32 v46, s[4:5], v42, v42, 2.0
	v_rcp_f32_e32 v47, v46
	v_mul_f32_e32 v45, 0x3fb8aa3b, v45
	v_exp_f32_e32 v44, v44
	v_exp_f32_e32 v45, v45
	v_fma_f32 v48, -v46, v47, 1.0
	v_fmac_f32_e32 v47, v48, v47
	v_div_scale_f32 v48, vcc, 2.0, v42, 2.0
	v_mul_f32_e32 v49, v48, v47
	v_fma_f32 v50, -v46, v49, v48
	v_fmac_f32_e32 v49, v50, v47
	v_fma_f32 v46, -v46, v49, v48
	v_div_fmas_f32 v46, v46, v47, v49
	v_pk_add_f32 v[44:45], v[44:45], 1.0 op_sel_hi:[1,0]
	v_div_fixup_f32 v42, v46, v42, 2.0
	v_div_scale_f32 v46, s[4:5], v45, v45, 2.0
	v_rcp_f32_e32 v47, v46
	v_pk_add_f32 v[42:43], v[42:43], 1.0 op_sel_hi:[1,0] neg_lo:[1,0] neg_hi:[1,0]
	v_fma_f32 v48, -v46, v47, 1.0
	v_fmac_f32_e32 v47, v48, v47
	v_div_scale_f32 v48, vcc, 2.0, v45, 2.0
	v_mul_f32_e32 v49, v48, v47
	v_fma_f32 v50, -v46, v49, v48
	v_fmac_f32_e32 v49, v50, v47
	v_fma_f32 v46, -v46, v49, v48
	v_div_fmas_f32 v46, v46, v47, v49
	v_div_fixup_f32 v45, v46, v45, 2.0
	v_div_scale_f32 v46, s[4:5], v44, v44, 2.0
	v_rcp_f32_e32 v47, v46
	s_nop 0
	v_fma_f32 v48, -v46, v47, 1.0
	v_fmac_f32_e32 v47, v48, v47
	v_div_scale_f32 v48, vcc, 2.0, v44, 2.0
	v_mul_f32_e32 v49, v48, v47
	v_fma_f32 v50, -v46, v49, v48
	v_fmac_f32_e32 v49, v50, v47
	v_fma_f32 v46, -v46, v49, v48
	v_div_fmas_f32 v46, v46, v47, v49
	v_div_fixup_f32 v44, v46, v44, 2.0
	v_sub_f32_e32 v47, v55, v21
	v_sub_f32_e32 v46, v54, v20
	v_pk_fma_f32 v[16:17], v[16:17], v[46:47], v[20:21]
	v_sub_f32_e32 v49, v59, v23
	v_add_f32_e32 v16, v16, v16
	v_add_f32_e32 v17, v17, v17
	v_mul_f32_e32 v16, 0x3fb8aa3b, v16
	v_mul_f32_e32 v17, 0x3fb8aa3b, v17
	v_exp_f32_e32 v16, v16
	v_exp_f32_e32 v17, v17
	v_sub_f32_e32 v48, v58, v22
	v_pk_fma_f32 v[18:19], v[18:19], v[48:49], v[22:23]
	v_pk_add_f32 v[44:45], v[44:45], 1.0 op_sel_hi:[1,0] neg_lo:[1,0] neg_hi:[1,0]
	v_pk_add_f32 v[16:17], v[16:17], 1.0 op_sel_hi:[1,0]
	s_nop 0
	v_div_scale_f32 v20, s[4:5], v17, v17, 2.0
	v_rcp_f32_e32 v21, v20
	s_nop 0
	v_fma_f32 v22, -v20, v21, 1.0
	v_fmac_f32_e32 v21, v22, v21
	v_div_scale_f32 v22, vcc, 2.0, v17, 2.0
	v_mul_f32_e32 v23, v22, v21
	v_fma_f32 v46, -v20, v23, v22
	v_fmac_f32_e32 v23, v46, v21
	v_fma_f32 v20, -v20, v23, v22
	v_div_fmas_f32 v20, v20, v21, v23
	v_div_fixup_f32 v17, v20, v17, 2.0
	v_div_scale_f32 v20, s[4:5], v16, v16, 2.0
	v_rcp_f32_e32 v21, v20
	s_nop 0
	v_fma_f32 v22, -v20, v21, 1.0
	v_fmac_f32_e32 v21, v22, v21
	v_div_scale_f32 v22, vcc, 2.0, v16, 2.0
	v_mul_f32_e32 v23, v22, v21
	v_fma_f32 v46, -v20, v23, v22
	v_fmac_f32_e32 v23, v46, v21
	v_fma_f32 v20, -v20, v23, v22
	v_div_fmas_f32 v20, v20, v21, v23
	v_div_fixup_f32 v16, v20, v16, 2.0
	v_pk_add_f32 v[20:21], v[16:17], 1.0 op_sel_hi:[1,0] neg_lo:[1,0] neg_hi:[1,0]
	v_add_f32_e32 v16, v18, v18
	v_add_f32_e32 v17, v19, v19
	v_mul_f32_e32 v16, 0x3fb8aa3b, v16
	v_mul_f32_e32 v17, 0x3fb8aa3b, v17
	v_exp_f32_e32 v16, v16
	v_exp_f32_e32 v17, v17
	s_nop 0
	v_pk_add_f32 v[16:17], v[16:17], 1.0 op_sel_hi:[1,0]
	s_nop 0
	v_div_scale_f32 v18, s[4:5], v17, v17, 2.0
	v_rcp_f32_e32 v19, v18
	s_nop 0
	v_fma_f32 v22, -v18, v19, 1.0
	v_fmac_f32_e32 v19, v22, v19
	v_div_scale_f32 v22, vcc, 2.0, v17, 2.0
	v_mul_f32_e32 v23, v22, v19
	v_fma_f32 v46, -v18, v23, v22
	v_fmac_f32_e32 v23, v46, v19
	v_fma_f32 v18, -v18, v23, v22
	v_div_fmas_f32 v18, v18, v19, v23
	v_div_fixup_f32 v17, v18, v17, 2.0
	v_div_scale_f32 v18, s[4:5], v16, v16, 2.0
	v_rcp_f32_e32 v19, v18
	s_nop 0
	v_fma_f32 v22, -v18, v19, 1.0
	v_fmac_f32_e32 v19, v22, v19
	v_div_scale_f32 v22, vcc, 2.0, v16, 2.0
	v_mul_f32_e32 v23, v22, v19
	v_fma_f32 v46, -v18, v23, v22
	v_fmac_f32_e32 v23, v46, v19
	v_fma_f32 v18, -v18, v23, v22
	v_div_fmas_f32 v18, v18, v19, v23
	v_div_fixup_f32 v16, v18, v16, 2.0
	v_pk_add_f32 v[22:23], v[16:17], 1.0 op_sel_hi:[1,0] neg_lo:[1,0] neg_hi:[1,0]
	v_cvt_pk_bf16_f32 v16, v42, v43
	v_cvt_pk_bf16_f32 v17, v44, v45
	v_cvt_pk_bf16_f32 v18, v20, v21
	v_cvt_pk_bf16_f32 v19, v22, v23
	s_waitcnt vmcnt(16)
	v_mov_b32_e32 v20, v128
	v_mov_b32_e32 v21, v129
	v_mov_b32_e32 v22, v130
	v_mov_b32_e32 v23, v131
	global_load_dwordx4 v[128:131], v[176:177], off offset:656
	v_lshlrev_b32_e32 v46, 16, v20
	v_and_b32_e32 v47, 0xffff0000, v20
	v_lshlrev_b32_e32 v48, 16, v21
	v_and_b32_e32 v49, 0xffff0000, v21
	v_lshl_add_u64 v[20:21], v[30:31], 0, v[186:187]
	v_lshlrev_b32_e32 v50, 16, v22
	v_and_b32_e32 v51, 0xffff0000, v22
	v_lshlrev_b32_e32 v52, 16, v23
	v_and_b32_e32 v53, 0xffff0000, v23
	s_waitcnt vmcnt(16)
	v_mov_b32_e32 v20, v132
	v_mov_b32_e32 v21, v133
	v_mov_b32_e32 v22, v134
	v_mov_b32_e32 v23, v135
	global_load_dwordx4 v[132:135], v[176:177], off offset:640
	v_cndmask_b32_e64 v23, v23, 0, s[36:37]
	v_cndmask_b32_e64 v22, v22, 0, s[36:37]
	v_cndmask_b32_e64 v21, v21, 0, s[36:37]
	v_cndmask_b32_e64 v20, v20, 0, s[36:37]
	v_lshlrev_b32_e32 v54, 16, v20
	v_and_b32_e32 v55, 0xffff0000, v20
	v_lshlrev_b32_e32 v58, 16, v21
	v_and_b32_e32 v59, 0xffff0000, v21
	v_lshlrev_b32_e32 v60, 16, v22
	v_and_b32_e32 v61, 0xffff0000, v22
	v_lshlrev_b32_e32 v62, 16, v23
	v_and_b32_e32 v63, 0xffff0000, v23
	s_waitcnt vmcnt(16)
	v_mov_b32_e32 v20, v136
	v_mov_b32_e32 v21, v137
	v_mov_b32_e32 v22, v138
	v_mov_b32_e32 v23, v139
	global_load_dwordx4 v[136:139], v236, s[74:75] offset:576
	s_waitcnt vmcnt(16)
	v_mov_b32_e32 v42, v140
	v_mov_b32_e32 v43, v141
	v_mov_b32_e32 v44, v142
	v_mov_b32_e32 v45, v143
	global_load_dwordx4 v[140:143], v237, s[74:75] offset:576
	v_sub_f32_e32 v55, v55, v47
	v_sub_f32_e32 v54, v54, v46
	v_sub_f32_e32 v59, v59, v49
	v_sub_f32_e32 v58, v58, v48
	v_pk_fma_f32 v[44:45], v[44:45], v[58:59], v[48:49]
	v_pk_fma_f32 v[42:43], v[42:43], v[54:55], v[46:47]
	v_sub_f32_e32 v47, v61, v51
	v_sub_f32_e32 v46, v60, v50
	v_sub_f32_e32 v49, v63, v53
	v_sub_f32_e32 v48, v62, v52
	v_pk_fma_f32 v[48:49], v[22:23], v[48:49], v[52:53]
	v_pk_fma_f32 v[22:23], v[20:21], v[46:47], v[50:51]
	v_cvt_pk_bf16_f32 v20, v42, v43
	v_cvt_pk_bf16_f32 v21, v44, v45
	v_cvt_pk_bf16_f32 v22, v22, v23
	v_cvt_pk_bf16_f32 v23, v48, v49
	s_waitcnt vmcnt(16)
	v_mov_b32_e32 v42, v144
	v_mov_b32_e32 v43, v145
	v_mov_b32_e32 v44, v146
	v_mov_b32_e32 v45, v147
	global_load_dwordx4 v[144:147], v238, s[74:75] offset:576
	v_lshl_add_u64 v[24:25], v[26:27], 0, v[188:189]
	s_waitcnt vmcnt(16)
	v_mov_b32_e32 v24, v148
	v_mov_b32_e32 v25, v149
	v_mov_b32_e32 v26, v150
	v_mov_b32_e32 v27, v151
	global_load_dwordx4 v[148:151], v[176:177], off offset:144
	v_lshlrev_b32_e32 v50, 16, v42
	v_and_b32_e32 v51, 0xffff0000, v42
	v_cndmask_b32_e64 v27, v27, 0, s[36:37]
	v_cndmask_b32_e64 v26, v26, 0, s[36:37]
	v_cndmask_b32_e64 v25, v25, 0, s[36:37]
	v_cndmask_b32_e64 v24, v24, 0, s[36:37]
	v_lshlrev_b32_e32 v54, 16, v24
	v_and_b32_e32 v55, 0xffff0000, v24
	v_lshlrev_b32_e32 v58, 16, v25
	v_and_b32_e32 v59, 0xffff0000, v25
	v_lshlrev_b32_e32 v60, 16, v26
	v_and_b32_e32 v61, 0xffff0000, v26
	v_lshlrev_b32_e32 v62, 16, v27
	v_and_b32_e32 v63, 0xffff0000, v27
	s_waitcnt vmcnt(16)
	v_mov_b32_e32 v24, v152
	v_mov_b32_e32 v25, v153
	v_mov_b32_e32 v26, v154
	v_mov_b32_e32 v27, v155
	global_load_dwordx4 v[152:155], v[176:177], off offset:128
	s_waitcnt vmcnt(16)
	v_mov_b32_e32 v46, v156
	v_mov_b32_e32 v47, v157
	v_mov_b32_e32 v48, v158
	v_mov_b32_e32 v49, v159
	global_load_dwordx4 v[156:159], v[176:177], off offset:784
	v_sub_f32_e32 v55, v55, v51
	v_sub_f32_e32 v54, v54, v50
	v_lshlrev_b32_e32 v52, 16, v43
	v_and_b32_e32 v53, 0xffff0000, v43
	v_sub_f32_e32 v59, v59, v53
	v_sub_f32_e32 v58, v58, v52
	v_lshlrev_b32_e32 v42, 16, v44
	v_and_b32_e32 v43, 0xffff0000, v44
	v_lshlrev_b32_e32 v44, 16, v45
	v_and_b32_e32 v45, 0xffff0000, v45
	v_pk_fma_f32 v[46:47], v[46:47], v[54:55], v[50:51]
	s_nop 0
	v_add_f32_e32 v46, v46, v46
	v_add_f32_e32 v47, v47, v47
	v_mul_f32_e32 v46, 0x3fb8aa3b, v46
	v_mul_f32_e32 v47, 0x3fb8aa3b, v47
	v_exp_f32_e32 v46, v46
	v_exp_f32_e32 v47, v47
	v_pk_fma_f32 v[48:49], v[48:49], v[58:59], v[52:53]
	v_pk_add_f32 v[46:47], v[46:47], 1.0 op_sel_hi:[1,0]
	s_nop 0
	v_div_scale_f32 v50, s[4:5], v47, v47, 2.0
	v_rcp_f32_e32 v51, v50
	v_add_f32_e32 v48, v48, v48
	v_add_f32_e32 v49, v49, v49
	v_mul_f32_e32 v48, 0x3fb8aa3b, v48
	v_fma_f32 v52, -v50, v51, 1.0
	v_fmac_f32_e32 v51, v52, v51
	v_div_scale_f32 v52, vcc, 2.0, v47, 2.0
	v_mul_f32_e32 v53, v52, v51
	v_fma_f32 v54, -v50, v53, v52
	v_fmac_f32_e32 v53, v54, v51
	v_fma_f32 v50, -v50, v53, v52
	v_div_fmas_f32 v50, v50, v51, v53
	v_div_fixup_f32 v47, v50, v47, 2.0
	v_div_scale_f32 v50, s[4:5], v46, v46, 2.0
	v_rcp_f32_e32 v51, v50
	v_mul_f32_e32 v49, 0x3fb8aa3b, v49
	v_exp_f32_e32 v48, v48
	v_exp_f32_e32 v49, v49
	v_fma_f32 v52, -v50, v51, 1.0
	v_fmac_f32_e32 v51, v52, v51
	v_div_scale_f32 v52, vcc, 2.0, v46, 2.0
	v_mul_f32_e32 v53, v52, v51
	v_fma_f32 v54, -v50, v53, v52
	v_fmac_f32_e32 v53, v54, v51
	v_fma_f32 v50, -v50, v53, v52
	v_div_fmas_f32 v50, v50, v51, v53
	v_pk_add_f32 v[48:49], v[48:49], 1.0 op_sel_hi:[1,0]
	v_div_fixup_f32 v46, v50, v46, 2.0
	v_div_scale_f32 v50, s[4:5], v49, v49, 2.0
	v_rcp_f32_e32 v51, v50
	v_pk_add_f32 v[46:47], v[46:47], 1.0 op_sel_hi:[1,0] neg_lo:[1,0] neg_hi:[1,0]
	v_fma_f32 v52, -v50, v51, 1.0
	v_fmac_f32_e32 v51, v52, v51
	v_div_scale_f32 v52, vcc, 2.0, v49, 2.0
	v_mul_f32_e32 v53, v52, v51
	v_fma_f32 v54, -v50, v53, v52
	v_fmac_f32_e32 v53, v54, v51
	v_fma_f32 v50, -v50, v53, v52
	v_div_fmas_f32 v50, v50, v51, v53
	v_div_fixup_f32 v49, v50, v49, 2.0
	v_div_scale_f32 v50, s[4:5], v48, v48, 2.0
	v_rcp_f32_e32 v51, v50
	s_nop 0
	v_fma_f32 v52, -v50, v51, 1.0
	v_fmac_f32_e32 v51, v52, v51
	v_div_scale_f32 v52, vcc, 2.0, v48, 2.0
	v_mul_f32_e32 v53, v52, v51
	v_fma_f32 v54, -v50, v53, v52
	v_fmac_f32_e32 v53, v54, v51
	v_fma_f32 v50, -v50, v53, v52
	v_div_fmas_f32 v50, v50, v51, v53
	v_div_fixup_f32 v48, v50, v48, 2.0
	v_sub_f32_e32 v51, v61, v43
	v_sub_f32_e32 v50, v60, v42
	v_pk_fma_f32 v[24:25], v[24:25], v[50:51], v[42:43]
	v_sub_f32_e32 v53, v63, v45
	v_add_f32_e32 v24, v24, v24
	v_add_f32_e32 v25, v25, v25
	v_mul_f32_e32 v24, 0x3fb8aa3b, v24
	v_mul_f32_e32 v25, 0x3fb8aa3b, v25
	v_exp_f32_e32 v24, v24
	v_exp_f32_e32 v25, v25
	v_sub_f32_e32 v52, v62, v44
	v_pk_fma_f32 v[26:27], v[26:27], v[52:53], v[44:45]
	v_pk_add_f32 v[48:49], v[48:49], 1.0 op_sel_hi:[1,0] neg_lo:[1,0] neg_hi:[1,0]
	v_pk_add_f32 v[24:25], v[24:25], 1.0 op_sel_hi:[1,0]
	s_nop 0
	v_div_scale_f32 v42, s[4:5], v25, v25, 2.0
	v_rcp_f32_e32 v43, v42
	s_nop 0
	v_fma_f32 v44, -v42, v43, 1.0
	v_fmac_f32_e32 v43, v44, v43
	v_div_scale_f32 v44, vcc, 2.0, v25, 2.0
	v_mul_f32_e32 v45, v44, v43
	v_fma_f32 v50, -v42, v45, v44
	v_fmac_f32_e32 v45, v50, v43
	v_fma_f32 v42, -v42, v45, v44
	v_div_fmas_f32 v42, v42, v43, v45
	v_div_fixup_f32 v25, v42, v25, 2.0
	v_div_scale_f32 v42, s[4:5], v24, v24, 2.0
	v_rcp_f32_e32 v43, v42
	s_nop 0
	v_fma_f32 v44, -v42, v43, 1.0
	v_fmac_f32_e32 v43, v44, v43
	v_div_scale_f32 v44, vcc, 2.0, v24, 2.0
	v_mul_f32_e32 v45, v44, v43
	v_fma_f32 v50, -v42, v45, v44
	v_fmac_f32_e32 v45, v50, v43
	v_fma_f32 v42, -v42, v45, v44
	v_div_fmas_f32 v42, v42, v43, v45
	v_div_fixup_f32 v24, v42, v24, 2.0
	v_pk_add_f32 v[42:43], v[24:25], 1.0 op_sel_hi:[1,0] neg_lo:[1,0] neg_hi:[1,0]
	v_add_f32_e32 v24, v26, v26
	v_add_f32_e32 v25, v27, v27
	v_mul_f32_e32 v24, 0x3fb8aa3b, v24
	v_mul_f32_e32 v25, 0x3fb8aa3b, v25
	v_exp_f32_e32 v24, v24
	v_exp_f32_e32 v25, v25
	s_nop 0
	v_pk_add_f32 v[24:25], v[24:25], 1.0 op_sel_hi:[1,0]
	s_nop 0
	v_div_scale_f32 v26, s[4:5], v25, v25, 2.0
	v_rcp_f32_e32 v27, v26
	s_nop 0
	v_fma_f32 v44, -v26, v27, 1.0
	v_fmac_f32_e32 v27, v44, v27
	v_div_scale_f32 v44, vcc, 2.0, v25, 2.0
	v_mul_f32_e32 v45, v44, v27
	v_fma_f32 v50, -v26, v45, v44
	v_fmac_f32_e32 v45, v50, v27
	v_fma_f32 v26, -v26, v45, v44
	v_div_fmas_f32 v26, v26, v27, v45
	v_div_fixup_f32 v25, v26, v25, 2.0
	v_div_scale_f32 v26, s[4:5], v24, v24, 2.0
	v_rcp_f32_e32 v27, v26
	s_mov_b64 s[4:5], 0x2c00
	v_fma_f32 v44, -v26, v27, 1.0
	v_fmac_f32_e32 v27, v44, v27
	v_div_scale_f32 v44, vcc, 2.0, v24, 2.0
	v_mul_f32_e32 v45, v44, v27
	v_fma_f32 v50, -v26, v45, v44
	v_fmac_f32_e32 v45, v50, v27
	v_fma_f32 v26, -v26, v45, v44
	v_div_fmas_f32 v26, v26, v27, v45
	v_div_fixup_f32 v24, v26, v24, 2.0
	v_pk_add_f32 v[44:45], v[24:25], 1.0 op_sel_hi:[1,0] neg_lo:[1,0] neg_hi:[1,0]
	v_cvt_pk_bf16_f32 v24, v46, v47
	v_cvt_pk_bf16_f32 v25, v48, v49
	v_cvt_pk_bf16_f32 v26, v42, v43
	v_cvt_pk_bf16_f32 v27, v44, v45
	s_waitcnt vmcnt(16)
	v_mov_b32_e32 v42, v160
	v_mov_b32_e32 v43, v161
	v_mov_b32_e32 v44, v162
	v_mov_b32_e32 v45, v163
	global_load_dwordx4 v[160:163], v[176:177], off offset:768
	v_lshl_add_u64 v[28:29], v[30:31], 0, v[188:189]
	s_waitcnt vmcnt(16)
	v_mov_b32_e32 v28, v210
	v_mov_b32_e32 v29, v211
	v_mov_b32_e32 v30, v212
	v_mov_b32_e32 v31, v213
	global_load_dwordx4 v[210:213], v236, s[74:75] offset:640
	v_lshlrev_b32_e32 v46, 16, v42
	v_and_b32_e32 v47, 0xffff0000, v42
	v_cndmask_b32_e64 v31, v31, 0, s[36:37]
	v_cndmask_b32_e64 v30, v30, 0, s[36:37]
	v_cndmask_b32_e64 v29, v29, 0, s[36:37]
	v_cndmask_b32_e64 v28, v28, 0, s[36:37]
	v_lshlrev_b32_e32 v48, 16, v43
	v_and_b32_e32 v49, 0xffff0000, v43
	v_lshlrev_b32_e32 v50, 16, v44
	v_and_b32_e32 v51, 0xffff0000, v44
	v_lshlrev_b32_e32 v52, 16, v45
	v_and_b32_e32 v53, 0xffff0000, v45
	v_lshlrev_b32_e32 v54, 16, v28
	v_and_b32_e32 v55, 0xffff0000, v28
	v_lshlrev_b32_e32 v58, 16, v29
	v_and_b32_e32 v59, 0xffff0000, v29
	v_lshlrev_b32_e32 v60, 16, v30
	v_and_b32_e32 v61, 0xffff0000, v30
	v_lshlrev_b32_e32 v62, 16, v31
	v_and_b32_e32 v63, 0xffff0000, v31
	s_waitcnt vmcnt(16)
	v_mov_b32_e32 v28, v232
	v_mov_b32_e32 v29, v233
	v_mov_b32_e32 v30, v234
	v_mov_b32_e32 v31, v235
	global_load_dwordx4 v[232:235], v237, s[74:75] offset:640
	s_waitcnt vmcnt(16)
	v_mov_b32_e32 v42, v240
	v_mov_b32_e32 v43, v241
	v_mov_b32_e32 v44, v242
	v_mov_b32_e32 v45, v243
	global_load_dwordx4 v[240:243], v238, s[74:75] offset:640
	v_sub_f32_e32 v55, v55, v47
	v_sub_f32_e32 v54, v54, v46
	v_sub_f32_e32 v59, v59, v49
	v_sub_f32_e32 v58, v58, v48
	v_pk_fma_f32 v[44:45], v[44:45], v[58:59], v[48:49]
	v_pk_fma_f32 v[42:43], v[42:43], v[54:55], v[46:47]
	v_sub_f32_e32 v47, v61, v51
	v_sub_f32_e32 v46, v60, v50
	v_sub_f32_e32 v49, v63, v53
	v_sub_f32_e32 v48, v62, v52
	v_pk_fma_f32 v[48:49], v[30:31], v[48:49], v[52:53]
	v_pk_fma_f32 v[30:31], v[28:29], v[46:47], v[50:51]
	v_cvt_pk_bf16_f32 v28, v42, v43
	v_cvt_pk_bf16_f32 v29, v44, v45
	v_cvt_pk_bf16_f32 v30, v30, v31
	v_cvt_pk_bf16_f32 v31, v48, v49
	v_lshl_add_u64 v[54:55], v[34:35], 0, s[4:5]
	s_waitcnt vmcnt(16)
	v_mov_b32_e32 v34, v244
	v_mov_b32_e32 v35, v245
	v_mov_b32_e32 v36, v246
	v_mov_b32_e32 v37, v247
	global_load_dwordx4 v[244:247], v[176:177], off offset:272
	v_lshl_add_u64 v[58:59], v[32:33], 0, s[4:5]
	v_add_co_u32_e32 v32, vcc, s79, v32
	v_lshl_add_u64 v[52:53], v[40:41], 0, s[4:5]
	s_nop 0
	v_addc_co_u32_e32 v33, vcc, 0, v33, vcc
	v_lshlrev_b32_e32 v48, 16, v34
	v_and_b32_e32 v49, 0xffff0000, v34
	v_lshlrev_b32_e32 v46, 16, v35
	v_and_b32_e32 v47, 0xffff0000, v35
	v_lshlrev_b32_e32 v44, 16, v36
	v_and_b32_e32 v45, 0xffff0000, v36
	v_lshlrev_b32_e32 v42, 16, v37
	v_and_b32_e32 v43, 0xffff0000, v37
	s_waitcnt vmcnt(16)
	v_mov_b32_e32 v34, v248
	v_mov_b32_e32 v35, v249
	v_mov_b32_e32 v36, v250
	v_mov_b32_e32 v37, v251
	global_load_dwordx4 v[248:251], v[176:177], off offset:256
	v_cndmask_b32_e64 v35, v35, 0, s[38:39]
	v_cndmask_b32_e64 v34, v34, 0, s[38:39]
	v_lshlrev_b32_e32 v70, 16, v34
	v_and_b32_e32 v71, 0xffff0000, v34
	v_lshlrev_b32_e32 v68, 16, v35
	v_and_b32_e32 v69, 0xffff0000, v35
	s_waitcnt vmcnt(16)
	v_mov_b32_e32 v32, v116
	v_mov_b32_e32 v33, v117
	v_mov_b32_e32 v34, v118
	v_mov_b32_e32 v35, v119
	global_load_dwordx4 v[116:119], v[176:177], off offset:912
	v_cndmask_b32_e64 v37, v37, 0, s[38:39]
	v_cndmask_b32_e64 v36, v36, 0, s[38:39]
	v_lshlrev_b32_e32 v40, 16, v36
	v_and_b32_e32 v41, 0xffff0000, v36
	v_lshlrev_b32_e32 v50, 16, v37
	v_and_b32_e32 v51, 0xffff0000, v37
	v_sub_f32_e32 v71, v71, v49
	v_sub_f32_e32 v70, v70, v48
	v_sub_f32_e32 v69, v69, v47
	v_sub_f32_e32 v68, v68, v46
	v_sub_f32_e32 v41, v41, v45
	v_sub_f32_e32 v40, v40, v44
	v_cndmask_b32_e64 v35, v35, 0, s[36:37]
	v_cndmask_b32_e64 v34, v34, 0, s[36:37]
	v_cndmask_b32_e64 v33, v33, 0, s[36:37]
	v_cndmask_b32_e64 v32, v32, 0, s[36:37]
	v_lshlrev_b32_e32 v72, 16, v32
	v_and_b32_e32 v73, 0xffff0000, v32
	v_lshlrev_b32_e32 v74, 16, v33
	v_and_b32_e32 v75, 0xffff0000, v33
	v_lshlrev_b32_e32 v76, 16, v34
	v_and_b32_e32 v77, 0xffff0000, v34
	v_lshlrev_b32_e32 v78, 16, v35
	v_and_b32_e32 v79, 0xffff0000, v35
	s_waitcnt vmcnt(16)
	v_mov_b32_e32 v32, v120
	v_mov_b32_e32 v33, v121
	v_mov_b32_e32 v34, v122
	v_mov_b32_e32 v35, v123
	global_load_dwordx4 v[120:123], v[176:177], off offset:896
	s_waitcnt vmcnt(16)
	v_mov_b32_e32 v60, v124
	v_mov_b32_e32 v61, v125
	v_mov_b32_e32 v62, v126
	v_mov_b32_e32 v63, v127
	global_load_dwordx4 v[124:127], v236, s[74:75] offset:704
	s_waitcnt vmcnt(16)
	v_mov_b32_e32 v36, v128
	v_mov_b32_e32 v37, v129
	v_mov_b32_e32 v38, v130
	v_mov_b32_e32 v39, v131
	global_load_dwordx4 v[128:131], v237, s[74:75] offset:704
	s_waitcnt vmcnt(16)
	v_mov_b32_e32 v64, v132
	v_mov_b32_e32 v65, v133
	v_mov_b32_e32 v66, v134
	v_mov_b32_e32 v67, v135
	global_load_dwordx4 v[132:135], v238, s[74:75] offset:704
	v_pk_fma_f32 v[32:33], v[32:33], v[40:41], v[44:45]
	v_pk_fma_f32 v[60:61], v[60:61], v[70:71], v[48:49]
	v_sub_f32_e32 v49, v73, v49
	v_sub_f32_e32 v48, v72, v48
	v_pk_fma_f32 v[48:49], v[64:65], v[48:49], v[60:61]
	v_pk_fma_f32 v[62:63], v[62:63], v[68:69], v[46:47]
	v_mul_f32_e32 v48, 0xbfb8aa3b, v48
	v_mul_f32_e32 v49, 0xbfb8aa3b, v49
	v_exp_f32_e32 v48, v48
	v_exp_f32_e32 v49, v49
	v_sub_f32_e32 v47, v75, v47
	v_sub_f32_e32 v46, v74, v46
	v_pk_fma_f32 v[46:47], v[66:67], v[46:47], v[62:63]
	v_pk_add_f32 v[48:49], v[48:49], 1.0 op_sel_hi:[1,0]
	v_mul_f32_e32 v46, 0xbfb8aa3b, v46
	v_div_scale_f32 v60, s[4:5], v49, v49, 1.0
	v_rcp_f32_e32 v61, v60
	v_mul_f32_e32 v47, 0xbfb8aa3b, v47
	v_exp_f32_e32 v46, v46
	v_exp_f32_e32 v47, v47
	v_fma_f32 v62, -v60, v61, 1.0
	v_fmac_f32_e32 v61, v62, v61
	v_div_scale_f32 v62, vcc, 1.0, v49, 1.0
	v_mul_f32_e32 v63, v62, v61
	v_fma_f32 v64, -v60, v63, v62
	v_fmac_f32_e32 v63, v64, v61
	v_fma_f32 v60, -v60, v63, v62
	v_div_fmas_f32 v60, v60, v61, v63
	v_div_fixup_f32 v49, v60, v49, 1.0
	v_div_scale_f32 v60, s[4:5], v48, v48, 1.0
	v_rcp_f32_e32 v61, v60
	v_pk_add_f32 v[46:47], v[46:47], 1.0 op_sel_hi:[1,0]
	v_sub_f32_e32 v41, v77, v45
	v_sub_f32_e32 v40, v76, v44
	v_fma_f32 v62, -v60, v61, 1.0
	v_fmac_f32_e32 v61, v62, v61
	v_div_scale_f32 v62, vcc, 1.0, v48, 1.0
	v_mul_f32_e32 v63, v62, v61
	v_fma_f32 v64, -v60, v63, v62
	v_fmac_f32_e32 v63, v64, v61
	v_fma_f32 v60, -v60, v63, v62
	v_div_fmas_f32 v60, v60, v61, v63
	v_div_fixup_f32 v48, v60, v48, 1.0
	v_div_scale_f32 v60, s[4:5], v47, v47, 1.0
	v_rcp_f32_e32 v61, v60
	v_pk_fma_f32 v[32:33], v[36:37], v[40:41], v[32:33]
	v_fma_f32 v62, -v60, v61, 1.0
	v_fmac_f32_e32 v61, v62, v61
	v_div_scale_f32 v62, vcc, 1.0, v47, 1.0
	v_mul_f32_e32 v63, v62, v61
	v_fma_f32 v64, -v60, v63, v62
	v_fmac_f32_e32 v63, v64, v61
	v_fma_f32 v60, -v60, v63, v62
	v_div_fmas_f32 v60, v60, v61, v63
	v_div_fixup_f32 v60, v60, v47, 1.0
	v_div_scale_f32 v47, s[4:5], v46, v46, 1.0
	v_rcp_f32_e32 v61, v47
	v_mul_f32_e32 v32, 0xbfb8aa3b, v32
	v_mul_f32_e32 v33, 0xbfb8aa3b, v33
	v_exp_f32_e32 v32, v32
	v_exp_f32_e32 v33, v33
	v_fma_f32 v62, -v47, v61, 1.0
	v_fmac_f32_e32 v61, v62, v61
	v_div_scale_f32 v62, vcc, 1.0, v46, 1.0
	v_mul_f32_e32 v63, v62, v61
	v_fma_f32 v64, -v47, v63, v62
	v_pk_add_f32 v[32:33], v[32:33], 1.0 op_sel_hi:[1,0]
	v_fmac_f32_e32 v63, v64, v61
	v_div_scale_f32 v36, s[4:5], v33, v33, 1.0
	v_fma_f32 v47, -v47, v63, v62
	v_rcp_f32_e32 v37, v36
	v_div_fmas_f32 v47, v47, v61, v63
	v_div_fixup_f32 v61, v47, v46, 1.0
	v_sub_f32_e32 v47, v51, v43
	v_sub_f32_e32 v46, v50, v42
	v_pk_fma_f32 v[34:35], v[34:35], v[46:47], v[42:43]
	v_sub_f32_e32 v43, v79, v43
	v_sub_f32_e32 v42, v78, v42
	v_pk_fma_f32 v[34:35], v[38:39], v[42:43], v[34:35]
	v_fma_f32 v38, -v36, v37, 1.0
	v_fmac_f32_e32 v37, v38, v37
	v_div_scale_f32 v38, vcc, 1.0, v33, 1.0
	v_mul_f32_e32 v39, v38, v37
	v_fma_f32 v40, -v36, v39, v38
	v_fmac_f32_e32 v39, v40, v37
	v_fma_f32 v36, -v36, v39, v38
	v_div_fmas_f32 v36, v36, v37, v39
	v_div_fixup_f32 v36, v36, v33, 1.0
	v_div_scale_f32 v33, s[4:5], v32, v32, 1.0
	v_rcp_f32_e32 v37, v33
	s_nop 0
	v_fma_f32 v38, -v33, v37, 1.0
	v_fmac_f32_e32 v37, v38, v37
	v_div_scale_f32 v38, vcc, 1.0, v32, 1.0
	v_mul_f32_e32 v39, v38, v37
	v_fma_f32 v40, -v33, v39, v38
	v_fmac_f32_e32 v39, v40, v37
	v_fma_f32 v33, -v33, v39, v38
	v_div_fmas_f32 v33, v33, v37, v39
	v_div_fixup_f32 v37, v33, v32, 1.0
	v_mul_f32_e32 v32, 0xbfb8aa3b, v34
	v_mul_f32_e32 v33, 0xbfb8aa3b, v35
	v_exp_f32_e32 v32, v32
	v_exp_f32_e32 v33, v33
	s_nop 0
	v_pk_add_f32 v[32:33], v[32:33], 1.0 op_sel_hi:[1,0]
	s_nop 0
	v_div_scale_f32 v34, s[4:5], v33, v33, 1.0
	v_rcp_f32_e32 v35, v34
	s_nop 0
	v_fma_f32 v38, -v34, v35, 1.0
	v_fmac_f32_e32 v35, v38, v35
	v_div_scale_f32 v38, vcc, 1.0, v33, 1.0
	v_mul_f32_e32 v39, v38, v35
	v_fma_f32 v40, -v34, v39, v38
	v_fmac_f32_e32 v39, v40, v35
	v_fma_f32 v34, -v34, v39, v38
	v_div_fmas_f32 v34, v34, v35, v39
	v_div_fixup_f32 v35, v34, v33, 1.0
	v_div_scale_f32 v33, s[4:5], v32, v32, 1.0
	v_rcp_f32_e32 v34, v33
	s_nop 0
	v_fma_f32 v38, -v33, v34, 1.0
	v_fmac_f32_e32 v34, v38, v34
	v_div_scale_f32 v38, vcc, 1.0, v32, 1.0
	v_mul_f32_e32 v39, v38, v34
	v_fma_f32 v40, -v33, v39, v38
	v_fmac_f32_e32 v39, v40, v34
	v_fma_f32 v33, -v33, v39, v38
	v_div_fmas_f32 v33, v33, v34, v39
	v_div_fixup_f32 v38, v33, v32, 1.0
	v_cvt_pk_bf16_f32 v32, v48, v49
	v_cvt_pk_bf16_f32 v33, v61, v60
	v_cvt_pk_bf16_f32 v34, v37, v36
	v_cvt_pk_bf16_f32 v35, v38, v35
	s_waitcnt vmcnt(16)
	v_mov_b32_e32 v36, v136
	v_mov_b32_e32 v37, v137
	v_mov_b32_e32 v38, v138
	v_mov_b32_e32 v39, v139
	global_load_dwordx4 v[136:139], v[176:177], off offset:400
	v_lshlrev_b32_e32 v50, 16, v36
	v_and_b32_e32 v51, 0xffff0000, v36
	v_lshlrev_b32_e32 v48, 16, v37
	v_and_b32_e32 v49, 0xffff0000, v37
	v_lshlrev_b32_e32 v46, 16, v38
	v_and_b32_e32 v47, 0xffff0000, v38
	v_lshlrev_b32_e32 v44, 16, v39
	v_and_b32_e32 v45, 0xffff0000, v39
	s_waitcnt vmcnt(16)
	v_mov_b32_e32 v36, v140
	v_mov_b32_e32 v37, v141
	v_mov_b32_e32 v38, v142
	v_mov_b32_e32 v39, v143
	global_load_dwordx4 v[140:143], v[176:177], off offset:384
	v_cndmask_b32_e64 v39, v39, 0, s[38:39]
	v_cndmask_b32_e64 v38, v38, 0, s[38:39]
	v_cndmask_b32_e64 v37, v37, 0, s[38:39]
	v_cndmask_b32_e64 v36, v36, 0, s[38:39]
	v_lshlrev_b32_e32 v72, 16, v36
	v_and_b32_e32 v73, 0xffff0000, v36
	v_lshlrev_b32_e32 v70, 16, v37
	v_and_b32_e32 v71, 0xffff0000, v37
	v_lshlrev_b32_e32 v60, 16, v38
	v_and_b32_e32 v61, 0xffff0000, v38
	v_lshlrev_b32_e32 v74, 16, v39
	v_and_b32_e32 v75, 0xffff0000, v39
	s_waitcnt vmcnt(16)
	v_mov_b32_e32 v36, v144
	v_mov_b32_e32 v37, v145
	v_mov_b32_e32 v38, v146
	v_mov_b32_e32 v39, v147
	global_load_dwordx4 v[144:147], v[176:177], off offset:1040
	v_sub_f32_e32 v73, v73, v51
	v_sub_f32_e32 v72, v72, v50
	v_sub_f32_e32 v71, v71, v49
	v_sub_f32_e32 v70, v70, v48
	v_cndmask_b32_e64 v39, v39, 0, s[36:37]
	v_cndmask_b32_e64 v38, v38, 0, s[36:37]
	v_cndmask_b32_e64 v37, v37, 0, s[36:37]
	v_cndmask_b32_e64 v36, v36, 0, s[36:37]
	v_lshlrev_b32_e32 v76, 16, v36
	v_and_b32_e32 v77, 0xffff0000, v36
	v_lshlrev_b32_e32 v78, 16, v37
	v_and_b32_e32 v79, 0xffff0000, v37
	v_lshlrev_b32_e32 v80, 16, v38
	v_and_b32_e32 v81, 0xffff0000, v38
	v_lshlrev_b32_e32 v82, 16, v39
	v_and_b32_e32 v83, 0xffff0000, v39
	s_waitcnt vmcnt(16)
	v_mov_b32_e32 v36, v148
	v_mov_b32_e32 v37, v149
	v_mov_b32_e32 v38, v150
	v_mov_b32_e32 v39, v151
	global_load_dwordx4 v[148:151], v[176:177], off offset:1024
	s_waitcnt vmcnt(16)
	v_mov_b32_e32 v62, v152
	v_mov_b32_e32 v63, v153
	v_mov_b32_e32 v64, v154
	v_mov_b32_e32 v65, v155
	global_load_dwordx4 v[152:155], v236, s[74:75] offset:768
	s_waitcnt vmcnt(16)
	v_mov_b32_e32 v40, v156
	v_mov_b32_e32 v41, v157
	v_mov_b32_e32 v42, v158
	v_mov_b32_e32 v43, v159
	global_load_dwordx4 v[156:159], v237, s[74:75] offset:768
	s_waitcnt vmcnt(16)
	v_mov_b32_e32 v66, v160
	v_mov_b32_e32 v67, v161
	v_mov_b32_e32 v68, v162
	v_mov_b32_e32 v69, v163
	global_load_dwordx4 v[160:163], v238, s[74:75] offset:768
	v_pk_fma_f32 v[62:63], v[62:63], v[72:73], v[50:51]
	v_sub_f32_e32 v51, v77, v51
	v_sub_f32_e32 v50, v76, v50
	v_pk_fma_f32 v[50:51], v[66:67], v[50:51], v[62:63]
	v_pk_fma_f32 v[64:65], v[64:65], v[70:71], v[48:49]
	v_mul_f32_e32 v50, 0xbfb8aa3b, v50
	v_mul_f32_e32 v51, 0xbfb8aa3b, v51
	v_exp_f32_e32 v50, v50
	v_exp_f32_e32 v51, v51
	v_sub_f32_e32 v49, v79, v49
	v_sub_f32_e32 v48, v78, v48
	v_pk_fma_f32 v[48:49], v[68:69], v[48:49], v[64:65]
	v_pk_add_f32 v[50:51], v[50:51], 1.0 op_sel_hi:[1,0]
	v_mul_f32_e32 v48, 0xbfb8aa3b, v48
	v_div_scale_f32 v62, s[4:5], v51, v51, 1.0
	v_rcp_f32_e32 v63, v62
	v_mul_f32_e32 v49, 0xbfb8aa3b, v49
	v_exp_f32_e32 v48, v48
	v_exp_f32_e32 v49, v49
	v_fma_f32 v64, -v62, v63, 1.0
	v_fmac_f32_e32 v63, v64, v63
	v_div_scale_f32 v64, vcc, 1.0, v51, 1.0
	v_mul_f32_e32 v65, v64, v63
	v_fma_f32 v66, -v62, v65, v64
	v_fmac_f32_e32 v65, v66, v63
	v_fma_f32 v62, -v62, v65, v64
	v_div_fmas_f32 v62, v62, v63, v65
	v_div_fixup_f32 v62, v62, v51, 1.0
	v_div_scale_f32 v51, s[4:5], v50, v50, 1.0
	v_rcp_f32_e32 v63, v51
	v_pk_add_f32 v[48:49], v[48:49], 1.0 op_sel_hi:[1,0]
	v_fma_f32 v64, -v51, v63, 1.0
	v_fmac_f32_e32 v63, v64, v63
	v_div_scale_f32 v64, vcc, 1.0, v50, 1.0
	v_mul_f32_e32 v65, v64, v63
	v_fma_f32 v66, -v51, v65, v64
	v_fmac_f32_e32 v65, v66, v63
	v_fma_f32 v51, -v51, v65, v64
	v_div_fmas_f32 v51, v51, v63, v65
	v_div_fixup_f32 v63, v51, v50, 1.0
	v_div_scale_f32 v50, s[4:5], v49, v49, 1.0
	v_rcp_f32_e32 v51, v50
	s_nop 0
	v_fma_f32 v64, -v50, v51, 1.0
	v_fmac_f32_e32 v51, v64, v51
	v_div_scale_f32 v64, vcc, 1.0, v49, 1.0
	v_mul_f32_e32 v65, v64, v51
	v_fma_f32 v66, -v50, v65, v64
	v_fmac_f32_e32 v65, v66, v51
	v_fma_f32 v50, -v50, v65, v64
	v_div_fmas_f32 v50, v50, v51, v65
	v_div_fixup_f32 v64, v50, v49, 1.0
	v_div_scale_f32 v49, s[4:5], v48, v48, 1.0
	v_rcp_f32_e32 v50, v49
	s_nop 0
	v_fma_f32 v51, -v49, v50, 1.0
	v_fmac_f32_e32 v50, v51, v50
	v_div_scale_f32 v51, vcc, 1.0, v48, 1.0
	v_mul_f32_e32 v65, v51, v50
	v_fma_f32 v66, -v49, v65, v51
	v_fmac_f32_e32 v65, v66, v50
	v_fma_f32 v49, -v49, v65, v51
	v_div_fmas_f32 v49, v49, v50, v65
	v_sub_f32_e32 v51, v61, v47
	v_sub_f32_e32 v50, v60, v46
	v_pk_fma_f32 v[36:37], v[36:37], v[50:51], v[46:47]
	v_sub_f32_e32 v47, v81, v47
	v_sub_f32_e32 v46, v80, v46
	v_pk_fma_f32 v[36:37], v[40:41], v[46:47], v[36:37]
	v_div_fixup_f32 v65, v49, v48, 1.0
	v_mul_f32_e32 v36, 0xbfb8aa3b, v36
	v_mul_f32_e32 v37, 0xbfb8aa3b, v37
	v_exp_f32_e32 v36, v36
	v_exp_f32_e32 v37, v37
	v_sub_f32_e32 v49, v75, v45
	v_sub_f32_e32 v48, v74, v44
	v_pk_fma_f32 v[38:39], v[38:39], v[48:49], v[44:45]
	v_pk_add_f32 v[36:37], v[36:37], 1.0 op_sel_hi:[1,0]
	v_sub_f32_e32 v45, v83, v45
	v_div_scale_f32 v40, s[4:5], v37, v37, 1.0
	v_rcp_f32_e32 v41, v40
	v_sub_f32_e32 v44, v82, v44
	v_pk_fma_f32 v[38:39], v[42:43], v[44:45], v[38:39]
	v_fma_f32 v42, -v40, v41, 1.0
	v_fmac_f32_e32 v41, v42, v41
	v_div_scale_f32 v42, vcc, 1.0, v37, 1.0
	v_mul_f32_e32 v43, v42, v41
	v_fma_f32 v44, -v40, v43, v42
	v_fmac_f32_e32 v43, v44, v41
	v_fma_f32 v40, -v40, v43, v42
	v_div_fmas_f32 v40, v40, v41, v43
	v_div_fixup_f32 v40, v40, v37, 1.0
	v_div_scale_f32 v37, s[4:5], v36, v36, 1.0
	v_rcp_f32_e32 v41, v37
	s_nop 0
	v_fma_f32 v42, -v37, v41, 1.0
	v_fmac_f32_e32 v41, v42, v41
	v_div_scale_f32 v42, vcc, 1.0, v36, 1.0
	v_mul_f32_e32 v43, v42, v41
	v_fma_f32 v44, -v37, v43, v42
	v_fmac_f32_e32 v43, v44, v41
	v_fma_f32 v37, -v37, v43, v42
	v_div_fmas_f32 v37, v37, v41, v43
	v_div_fixup_f32 v41, v37, v36, 1.0
	v_mul_f32_e32 v36, 0xbfb8aa3b, v38
	v_mul_f32_e32 v37, 0xbfb8aa3b, v39
	v_exp_f32_e32 v36, v36
	v_exp_f32_e32 v37, v37
	s_nop 0
	v_pk_add_f32 v[36:37], v[36:37], 1.0 op_sel_hi:[1,0]
	s_nop 0
	v_div_scale_f32 v38, s[4:5], v37, v37, 1.0
	v_rcp_f32_e32 v39, v38
	s_nop 0
	v_fma_f32 v42, -v38, v39, 1.0
	v_fmac_f32_e32 v39, v42, v39
	v_div_scale_f32 v42, vcc, 1.0, v37, 1.0
	v_mul_f32_e32 v43, v42, v39
	v_fma_f32 v44, -v38, v43, v42
	v_fmac_f32_e32 v43, v44, v39
	v_fma_f32 v38, -v38, v43, v42
	v_div_fmas_f32 v38, v38, v39, v43
	v_div_fixup_f32 v39, v38, v37, 1.0
	v_div_scale_f32 v37, s[4:5], v36, v36, 1.0
	v_rcp_f32_e32 v38, v37
	s_nop 0
	v_fma_f32 v42, -v37, v38, 1.0
	v_fmac_f32_e32 v38, v42, v38
	v_div_scale_f32 v42, vcc, 1.0, v36, 1.0
	v_mul_f32_e32 v43, v42, v38
	v_fma_f32 v44, -v37, v43, v42
	v_fmac_f32_e32 v43, v44, v38
	v_fma_f32 v37, -v37, v43, v42
	v_div_fmas_f32 v37, v37, v38, v43
	v_div_fixup_f32 v42, v37, v36, 1.0
	v_cvt_pk_bf16_f32 v36, v63, v62
	v_cvt_pk_bf16_f32 v37, v65, v64
	v_cvt_pk_bf16_f32 v38, v41, v40
	v_cvt_pk_bf16_f32 v39, v42, v39
	s_waitcnt vmcnt(16)
	v_mov_b32_e32 v40, v210
	v_mov_b32_e32 v41, v211
	v_mov_b32_e32 v42, v212
	v_mov_b32_e32 v43, v213
	global_load_dwordx4 v[210:213], v[176:177], off offset:528
	v_lshlrev_b32_e32 v62, 16, v40
	v_and_b32_e32 v63, 0xffff0000, v40
	v_lshlrev_b32_e32 v60, 16, v41
	v_and_b32_e32 v61, 0xffff0000, v41
	v_lshlrev_b32_e32 v50, 16, v42
	v_and_b32_e32 v51, 0xffff0000, v42
	v_lshlrev_b32_e32 v48, 16, v43
	v_and_b32_e32 v49, 0xffff0000, v43
	s_waitcnt vmcnt(16)
	v_mov_b32_e32 v40, v232
	v_mov_b32_e32 v41, v233
	v_mov_b32_e32 v42, v234
	v_mov_b32_e32 v43, v235
	global_load_dwordx4 v[232:235], v[176:177], off offset:512
	v_cndmask_b32_e64 v43, v43, 0, s[38:39]
	v_cndmask_b32_e64 v42, v42, 0, s[38:39]
	v_cndmask_b32_e64 v41, v41, 0, s[38:39]
	v_cndmask_b32_e64 v40, v40, 0, s[38:39]
	v_lshlrev_b32_e32 v76, 16, v40
	v_and_b32_e32 v77, 0xffff0000, v40
	v_lshlrev_b32_e32 v74, 16, v41
	v_and_b32_e32 v75, 0xffff0000, v41
	v_lshlrev_b32_e32 v64, 16, v42
	v_and_b32_e32 v65, 0xffff0000, v42
	v_lshlrev_b32_e32 v78, 16, v43
	v_and_b32_e32 v79, 0xffff0000, v43
	s_waitcnt vmcnt(16)
	v_mov_b32_e32 v40, v240
	v_mov_b32_e32 v41, v241
	v_mov_b32_e32 v42, v242
	v_mov_b32_e32 v43, v243
	global_load_dwordx4 v[240:243], v[176:177], off offset:1168
	v_sub_f32_e32 v77, v77, v63
	v_sub_f32_e32 v76, v76, v62
	v_sub_f32_e32 v75, v75, v61
	v_sub_f32_e32 v74, v74, v60
	v_cndmask_b32_e64 v43, v43, 0, s[36:37]
	v_cndmask_b32_e64 v42, v42, 0, s[36:37]
	v_cndmask_b32_e64 v41, v41, 0, s[36:37]
	v_cndmask_b32_e64 v40, v40, 0, s[36:37]
	v_lshlrev_b32_e32 v80, 16, v40
	v_and_b32_e32 v81, 0xffff0000, v40
	v_lshlrev_b32_e32 v82, 16, v41
	v_and_b32_e32 v83, 0xffff0000, v41
	v_lshlrev_b32_e32 v84, 16, v42
	v_and_b32_e32 v85, 0xffff0000, v42
	v_lshlrev_b32_e32 v86, 16, v43
	v_and_b32_e32 v87, 0xffff0000, v43
	s_waitcnt vmcnt(16)
	v_mov_b32_e32 v40, v244
	v_mov_b32_e32 v41, v245
	v_mov_b32_e32 v42, v246
	v_mov_b32_e32 v43, v247
	global_load_dwordx4 v[244:247], v[176:177], off offset:1152
	s_waitcnt vmcnt(16)
	v_mov_b32_e32 v66, v248
	v_mov_b32_e32 v67, v249
	v_mov_b32_e32 v68, v250
	v_mov_b32_e32 v69, v251
	s_waitcnt vmcnt(15)
	v_mov_b32_e32 v44, v116
	v_mov_b32_e32 v45, v117
	v_mov_b32_e32 v46, v118
	v_mov_b32_e32 v47, v119
	s_waitcnt vmcnt(14)
	v_mov_b32_e32 v70, v120
	v_mov_b32_e32 v71, v121
	v_mov_b32_e32 v72, v122
	v_mov_b32_e32 v73, v123
	v_pk_fma_f32 v[66:67], v[66:67], v[76:77], v[62:63]
	v_sub_f32_e32 v63, v81, v63
	v_sub_f32_e32 v62, v80, v62
	v_pk_fma_f32 v[62:63], v[70:71], v[62:63], v[66:67]
	v_pk_fma_f32 v[68:69], v[68:69], v[74:75], v[60:61]
	v_mul_f32_e32 v62, 0xbfb8aa3b, v62
	v_mul_f32_e32 v63, 0xbfb8aa3b, v63
	v_exp_f32_e32 v62, v62
	v_exp_f32_e32 v63, v63
	v_sub_f32_e32 v61, v83, v61
	v_sub_f32_e32 v60, v82, v60
	v_pk_fma_f32 v[60:61], v[72:73], v[60:61], v[68:69]
	v_pk_add_f32 v[62:63], v[62:63], 1.0 op_sel_hi:[1,0]
	v_mul_f32_e32 v60, 0xbfb8aa3b, v60
	v_div_scale_f32 v66, s[4:5], v63, v63, 1.0
	v_rcp_f32_e32 v67, v66
	v_mul_f32_e32 v61, 0xbfb8aa3b, v61
	v_exp_f32_e32 v60, v60
	v_exp_f32_e32 v61, v61
	v_fma_f32 v68, -v66, v67, 1.0
	v_fmac_f32_e32 v67, v68, v67
	v_div_scale_f32 v68, vcc, 1.0, v63, 1.0
	v_mul_f32_e32 v69, v68, v67
	v_fma_f32 v70, -v66, v69, v68
	v_fmac_f32_e32 v69, v70, v67
	v_fma_f32 v66, -v66, v69, v68
	v_div_fmas_f32 v66, v66, v67, v69
	v_div_fixup_f32 v66, v66, v63, 1.0
	v_div_scale_f32 v63, s[4:5], v62, v62, 1.0
	v_rcp_f32_e32 v67, v63
	v_pk_add_f32 v[60:61], v[60:61], 1.0 op_sel_hi:[1,0]
	v_fma_f32 v68, -v63, v67, 1.0
	v_fmac_f32_e32 v67, v68, v67
	v_div_scale_f32 v68, vcc, 1.0, v62, 1.0
	v_mul_f32_e32 v69, v68, v67
	v_fma_f32 v70, -v63, v69, v68
	v_fmac_f32_e32 v69, v70, v67
	v_fma_f32 v63, -v63, v69, v68
	v_div_fmas_f32 v63, v63, v67, v69
	v_div_fixup_f32 v67, v63, v62, 1.0
	v_div_scale_f32 v62, s[4:5], v61, v61, 1.0
	v_rcp_f32_e32 v63, v62
	s_nop 0
	v_fma_f32 v68, -v62, v63, 1.0
	v_fmac_f32_e32 v63, v68, v63
	v_div_scale_f32 v68, vcc, 1.0, v61, 1.0
	v_mul_f32_e32 v69, v68, v63
	v_fma_f32 v70, -v62, v69, v68
	v_fmac_f32_e32 v69, v70, v63
	v_fma_f32 v62, -v62, v69, v68
	v_div_fmas_f32 v62, v62, v63, v69
	v_div_fixup_f32 v68, v62, v61, 1.0
	v_div_scale_f32 v61, s[4:5], v60, v60, 1.0
	v_rcp_f32_e32 v62, v61
	s_nop 0
	v_fma_f32 v63, -v61, v62, 1.0
	v_fmac_f32_e32 v62, v63, v62
	v_div_scale_f32 v63, vcc, 1.0, v60, 1.0
	v_mul_f32_e32 v69, v63, v62
	v_fma_f32 v70, -v61, v69, v63
	v_fmac_f32_e32 v69, v70, v62
	v_fma_f32 v61, -v61, v69, v63
	v_div_fmas_f32 v61, v61, v62, v69
	v_sub_f32_e32 v63, v65, v51
	v_sub_f32_e32 v62, v64, v50
	v_pk_fma_f32 v[40:41], v[40:41], v[62:63], v[50:51]
	v_sub_f32_e32 v51, v85, v51
	v_sub_f32_e32 v50, v84, v50
	v_pk_fma_f32 v[40:41], v[44:45], v[50:51], v[40:41]
	v_div_fixup_f32 v69, v61, v60, 1.0
	v_mul_f32_e32 v40, 0xbfb8aa3b, v40
	v_mul_f32_e32 v41, 0xbfb8aa3b, v41
	v_exp_f32_e32 v40, v40
	v_exp_f32_e32 v41, v41
	v_sub_f32_e32 v61, v79, v49
	v_sub_f32_e32 v60, v78, v48
	v_pk_fma_f32 v[42:43], v[42:43], v[60:61], v[48:49]
	v_pk_add_f32 v[40:41], v[40:41], 1.0 op_sel_hi:[1,0]
	v_sub_f32_e32 v49, v87, v49
	v_div_scale_f32 v44, s[4:5], v41, v41, 1.0
	v_rcp_f32_e32 v45, v44
	v_sub_f32_e32 v48, v86, v48
	v_pk_fma_f32 v[42:43], v[46:47], v[48:49], v[42:43]
	v_fma_f32 v46, -v44, v45, 1.0
	v_fmac_f32_e32 v45, v46, v45
	v_div_scale_f32 v46, vcc, 1.0, v41, 1.0
	v_mul_f32_e32 v47, v46, v45
	v_fma_f32 v48, -v44, v47, v46
	v_fmac_f32_e32 v47, v48, v45
	v_fma_f32 v44, -v44, v47, v46
	v_div_fmas_f32 v44, v44, v45, v47
	v_div_fixup_f32 v44, v44, v41, 1.0
	v_div_scale_f32 v41, s[4:5], v40, v40, 1.0
	v_rcp_f32_e32 v45, v41
	s_nop 0
	v_fma_f32 v46, -v41, v45, 1.0
	v_fmac_f32_e32 v45, v46, v45
	v_div_scale_f32 v46, vcc, 1.0, v40, 1.0
	v_mul_f32_e32 v47, v46, v45
	v_fma_f32 v48, -v41, v47, v46
	v_fmac_f32_e32 v47, v48, v45
	v_fma_f32 v41, -v41, v47, v46
	v_div_fmas_f32 v41, v41, v45, v47
	v_div_fixup_f32 v45, v41, v40, 1.0
	v_mul_f32_e32 v40, 0xbfb8aa3b, v42
	v_mul_f32_e32 v41, 0xbfb8aa3b, v43
	v_exp_f32_e32 v40, v40
	v_exp_f32_e32 v41, v41
	s_nop 0
	v_pk_add_f32 v[40:41], v[40:41], 1.0 op_sel_hi:[1,0]
	s_nop 0
	v_div_scale_f32 v42, s[4:5], v41, v41, 1.0
	v_rcp_f32_e32 v43, v42
	s_nop 0
	v_fma_f32 v46, -v42, v43, 1.0
	v_fmac_f32_e32 v43, v46, v43
	v_div_scale_f32 v46, vcc, 1.0, v41, 1.0
	v_mul_f32_e32 v47, v46, v43
	v_fma_f32 v48, -v42, v47, v46
	v_fmac_f32_e32 v47, v48, v43
	v_fma_f32 v42, -v42, v47, v46
	v_div_fmas_f32 v42, v42, v43, v47
	v_div_fixup_f32 v43, v42, v41, 1.0
	v_div_scale_f32 v41, s[4:5], v40, v40, 1.0
	v_rcp_f32_e32 v42, v41
	s_nop 0
	v_fma_f32 v46, -v41, v42, 1.0
	v_fmac_f32_e32 v42, v46, v42
	v_div_scale_f32 v46, vcc, 1.0, v40, 1.0
	v_mul_f32_e32 v47, v46, v42
	v_fma_f32 v48, -v41, v47, v46
	v_fmac_f32_e32 v47, v48, v42
	v_fma_f32 v41, -v41, v47, v46
	v_div_fmas_f32 v41, v41, v42, v47
	v_div_fixup_f32 v46, v41, v40, 1.0
	v_cvt_pk_bf16_f32 v40, v67, v66
	v_cvt_pk_bf16_f32 v41, v69, v68
	v_cvt_pk_bf16_f32 v42, v45, v44
	v_cvt_pk_bf16_f32 v43, v46, v43
	s_waitcnt vmcnt(13)
	v_mov_b32_e32 v44, v124
	v_mov_b32_e32 v45, v125
	v_mov_b32_e32 v46, v126
	v_mov_b32_e32 v47, v127
	v_lshlrev_b32_e32 v66, 16, v44
	v_and_b32_e32 v67, 0xffff0000, v44
	v_lshlrev_b32_e32 v64, 16, v45
	v_and_b32_e32 v65, 0xffff0000, v45
	v_lshlrev_b32_e32 v62, 16, v46
	v_and_b32_e32 v63, 0xffff0000, v46
	v_lshlrev_b32_e32 v60, 16, v47
	v_and_b32_e32 v61, 0xffff0000, v47
	s_waitcnt vmcnt(12)
	v_mov_b32_e32 v44, v128
	v_mov_b32_e32 v45, v129
	v_mov_b32_e32 v46, v130
	v_mov_b32_e32 v47, v131
	v_cndmask_b32_e64 v47, v47, 0, s[38:39]
	v_cndmask_b32_e64 v46, v46, 0, s[38:39]
	v_cndmask_b32_e64 v45, v45, 0, s[38:39]
	v_cndmask_b32_e64 v44, v44, 0, s[38:39]
	v_lshlrev_b32_e32 v80, 16, v44
	v_and_b32_e32 v81, 0xffff0000, v44
	v_lshlrev_b32_e32 v78, 16, v45
	v_and_b32_e32 v79, 0xffff0000, v45
	v_lshlrev_b32_e32 v68, 16, v46
	v_and_b32_e32 v69, 0xffff0000, v46
	v_lshlrev_b32_e32 v82, 16, v47
	v_and_b32_e32 v83, 0xffff0000, v47
	s_waitcnt vmcnt(11)
	v_mov_b32_e32 v44, v132
	v_mov_b32_e32 v45, v133
	v_mov_b32_e32 v46, v134
	v_mov_b32_e32 v47, v135
	v_sub_f32_e32 v81, v81, v67
	v_sub_f32_e32 v80, v80, v66
	v_sub_f32_e32 v79, v79, v65
	v_sub_f32_e32 v78, v78, v64
	v_cndmask_b32_e64 v47, v47, 0, s[36:37]
	v_cndmask_b32_e64 v46, v46, 0, s[36:37]
	v_cndmask_b32_e64 v45, v45, 0, s[36:37]
	v_cndmask_b32_e64 v44, v44, 0, s[36:37]
	v_lshlrev_b32_e32 v84, 16, v44
	v_and_b32_e32 v85, 0xffff0000, v44
	v_lshlrev_b32_e32 v86, 16, v45
	v_and_b32_e32 v87, 0xffff0000, v45
	v_lshlrev_b32_e32 v88, 16, v46
	v_and_b32_e32 v89, 0xffff0000, v46
	v_lshlrev_b32_e32 v90, 16, v47
	v_and_b32_e32 v91, 0xffff0000, v47
	s_waitcnt vmcnt(10)
	v_mov_b32_e32 v44, v136
	v_mov_b32_e32 v45, v137
	v_mov_b32_e32 v46, v138
	v_mov_b32_e32 v47, v139
	s_waitcnt vmcnt(9)
	v_mov_b32_e32 v70, v140
	v_mov_b32_e32 v71, v141
	v_mov_b32_e32 v72, v142
	v_mov_b32_e32 v73, v143
	s_waitcnt vmcnt(8)
	v_mov_b32_e32 v48, v144
	v_mov_b32_e32 v49, v145
	v_mov_b32_e32 v50, v146
	v_mov_b32_e32 v51, v147
	s_waitcnt vmcnt(7)
	v_mov_b32_e32 v74, v148
	v_mov_b32_e32 v75, v149
	v_mov_b32_e32 v76, v150
	v_mov_b32_e32 v77, v151
	v_pk_fma_f32 v[70:71], v[70:71], v[80:81], v[66:67]
	v_sub_f32_e32 v67, v85, v67
	v_sub_f32_e32 v66, v84, v66
	v_pk_fma_f32 v[66:67], v[74:75], v[66:67], v[70:71]
	v_pk_fma_f32 v[72:73], v[72:73], v[78:79], v[64:65]
	v_mul_f32_e32 v66, 0xbfb8aa3b, v66
	v_mul_f32_e32 v67, 0xbfb8aa3b, v67
	v_exp_f32_e32 v66, v66
	v_exp_f32_e32 v67, v67
	v_sub_f32_e32 v65, v87, v65
	v_sub_f32_e32 v64, v86, v64
	v_pk_fma_f32 v[64:65], v[76:77], v[64:65], v[72:73]
	v_pk_add_f32 v[66:67], v[66:67], 1.0 op_sel_hi:[1,0]
	v_mul_f32_e32 v64, 0xbfb8aa3b, v64
	v_div_scale_f32 v70, s[4:5], v67, v67, 1.0
	v_rcp_f32_e32 v71, v70
	v_mul_f32_e32 v65, 0xbfb8aa3b, v65
	v_exp_f32_e32 v64, v64
	v_exp_f32_e32 v65, v65
	v_fma_f32 v72, -v70, v71, 1.0
	v_fmac_f32_e32 v71, v72, v71
	v_div_scale_f32 v72, vcc, 1.0, v67, 1.0
	v_mul_f32_e32 v73, v72, v71
	v_fma_f32 v74, -v70, v73, v72
	v_fmac_f32_e32 v73, v74, v71
	v_fma_f32 v70, -v70, v73, v72
	v_div_fmas_f32 v70, v70, v71, v73
	v_div_fixup_f32 v70, v70, v67, 1.0
	v_div_scale_f32 v67, s[4:5], v66, v66, 1.0
	v_rcp_f32_e32 v71, v67
	v_pk_add_f32 v[64:65], v[64:65], 1.0 op_sel_hi:[1,0]
	v_fma_f32 v72, -v67, v71, 1.0
	v_fmac_f32_e32 v71, v72, v71
	v_div_scale_f32 v72, vcc, 1.0, v66, 1.0
	v_mul_f32_e32 v73, v72, v71
	v_fma_f32 v74, -v67, v73, v72
	v_fmac_f32_e32 v73, v74, v71
	v_fma_f32 v67, -v67, v73, v72
	v_div_fmas_f32 v67, v67, v71, v73
	v_div_fixup_f32 v71, v67, v66, 1.0
	v_div_scale_f32 v66, s[4:5], v65, v65, 1.0
	v_rcp_f32_e32 v67, v66
	s_nop 0
	v_fma_f32 v72, -v66, v67, 1.0
	v_fmac_f32_e32 v67, v72, v67
	v_div_scale_f32 v72, vcc, 1.0, v65, 1.0
	v_mul_f32_e32 v73, v72, v67
	v_fma_f32 v74, -v66, v73, v72
	v_fmac_f32_e32 v73, v74, v67
	v_fma_f32 v66, -v66, v73, v72
	v_div_fmas_f32 v66, v66, v67, v73
	v_div_fixup_f32 v72, v66, v65, 1.0
	v_div_scale_f32 v65, s[4:5], v64, v64, 1.0
	v_rcp_f32_e32 v66, v65
	s_nop 0
	v_fma_f32 v67, -v65, v66, 1.0
	v_fmac_f32_e32 v66, v67, v66
	v_div_scale_f32 v67, vcc, 1.0, v64, 1.0
	v_mul_f32_e32 v73, v67, v66
	v_fma_f32 v74, -v65, v73, v67
	v_fmac_f32_e32 v73, v74, v66
	v_fma_f32 v65, -v65, v73, v67
	v_div_fmas_f32 v65, v65, v66, v73
	v_sub_f32_e32 v67, v69, v63
	v_sub_f32_e32 v66, v68, v62
	v_pk_fma_f32 v[44:45], v[44:45], v[66:67], v[62:63]
	v_sub_f32_e32 v63, v89, v63
	v_sub_f32_e32 v62, v88, v62
	v_pk_fma_f32 v[44:45], v[48:49], v[62:63], v[44:45]
	v_div_fixup_f32 v73, v65, v64, 1.0
	v_mul_f32_e32 v44, 0xbfb8aa3b, v44
	v_mul_f32_e32 v45, 0xbfb8aa3b, v45
	v_exp_f32_e32 v44, v44
	v_exp_f32_e32 v45, v45
	v_sub_f32_e32 v65, v83, v61
	v_sub_f32_e32 v64, v82, v60
	v_pk_fma_f32 v[46:47], v[46:47], v[64:65], v[60:61]
	v_pk_add_f32 v[44:45], v[44:45], 1.0 op_sel_hi:[1,0]
	v_sub_f32_e32 v61, v91, v61
	v_div_scale_f32 v48, s[4:5], v45, v45, 1.0
	v_rcp_f32_e32 v49, v48
	v_sub_f32_e32 v60, v90, v60
	v_pk_fma_f32 v[46:47], v[50:51], v[60:61], v[46:47]
	v_fma_f32 v50, -v48, v49, 1.0
	v_fmac_f32_e32 v49, v50, v49
	v_div_scale_f32 v50, vcc, 1.0, v45, 1.0
	v_mul_f32_e32 v51, v50, v49
	v_fma_f32 v60, -v48, v51, v50
	v_fmac_f32_e32 v51, v60, v49
	v_fma_f32 v48, -v48, v51, v50
	v_div_fmas_f32 v48, v48, v49, v51
	v_div_fixup_f32 v48, v48, v45, 1.0
	v_div_scale_f32 v45, s[4:5], v44, v44, 1.0
	v_rcp_f32_e32 v49, v45
	s_nop 0
	v_fma_f32 v50, -v45, v49, 1.0
	v_fmac_f32_e32 v49, v50, v49
	v_div_scale_f32 v50, vcc, 1.0, v44, 1.0
	v_mul_f32_e32 v51, v50, v49
	v_fma_f32 v60, -v45, v51, v50
	v_fmac_f32_e32 v51, v60, v49
	v_fma_f32 v45, -v45, v51, v50
	v_div_fmas_f32 v45, v45, v49, v51
	v_div_fixup_f32 v49, v45, v44, 1.0
	v_mul_f32_e32 v44, 0xbfb8aa3b, v46
	v_mul_f32_e32 v45, 0xbfb8aa3b, v47
	v_exp_f32_e32 v44, v44
	v_exp_f32_e32 v45, v45
	s_nop 0
	v_pk_add_f32 v[44:45], v[44:45], 1.0 op_sel_hi:[1,0]
	s_nop 0
	v_div_scale_f32 v46, s[4:5], v45, v45, 1.0
	v_rcp_f32_e32 v47, v46
	s_nop 0
	v_fma_f32 v50, -v46, v47, 1.0
	v_fmac_f32_e32 v47, v50, v47
	v_div_scale_f32 v50, vcc, 1.0, v45, 1.0
	v_mul_f32_e32 v51, v50, v47
	v_fma_f32 v60, -v46, v51, v50
	v_fmac_f32_e32 v51, v60, v47
	v_fma_f32 v46, -v46, v51, v50
	v_div_fmas_f32 v46, v46, v47, v51
	v_div_fixup_f32 v47, v46, v45, 1.0
	v_div_scale_f32 v45, s[4:5], v44, v44, 1.0
	v_rcp_f32_e32 v46, v45
	s_nop 0
	v_fma_f32 v50, -v45, v46, 1.0
	v_fmac_f32_e32 v46, v50, v46
	v_div_scale_f32 v50, vcc, 1.0, v44, 1.0
	v_mul_f32_e32 v51, v50, v46
	v_fma_f32 v60, -v45, v51, v50
	v_fmac_f32_e32 v51, v60, v46
	v_fma_f32 v45, -v45, v51, v50
	v_div_fmas_f32 v45, v45, v46, v51
	v_div_fixup_f32 v50, v45, v44, 1.0
	v_cvt_pk_bf16_f32 v44, v71, v70
	v_cvt_pk_bf16_f32 v45, v73, v72
	v_cvt_pk_bf16_f32 v46, v49, v48
	v_cvt_pk_bf16_f32 v47, v50, v47
	s_waitcnt vmcnt(6)
	v_mov_b32_e32 v48, v152
	v_mov_b32_e32 v49, v153
	v_mov_b32_e32 v50, v154
	v_mov_b32_e32 v51, v155
	v_lshlrev_b32_e32 v66, 16, v48
	v_and_b32_e32 v67, 0xffff0000, v48
	v_lshlrev_b32_e32 v64, 16, v49
	v_and_b32_e32 v65, 0xffff0000, v49
	v_lshlrev_b32_e32 v62, 16, v50
	v_and_b32_e32 v63, 0xffff0000, v50
	v_lshlrev_b32_e32 v60, 16, v51
	v_and_b32_e32 v61, 0xffff0000, v51
	s_waitcnt vmcnt(5)
	v_mov_b32_e32 v48, v156
	v_mov_b32_e32 v49, v157
	v_mov_b32_e32 v50, v158
	v_mov_b32_e32 v51, v159
	v_cndmask_b32_e64 v51, v51, 0, s[38:39]
	v_cndmask_b32_e64 v50, v50, 0, s[38:39]
	v_cndmask_b32_e64 v49, v49, 0, s[38:39]
	v_cndmask_b32_e64 v48, v48, 0, s[38:39]
	v_lshlrev_b32_e32 v78, 16, v48
	v_and_b32_e32 v79, 0xffff0000, v48
	v_lshlrev_b32_e32 v80, 16, v49
	v_and_b32_e32 v81, 0xffff0000, v49
	v_lshlrev_b32_e32 v68, 16, v50
	v_and_b32_e32 v69, 0xffff0000, v50
	v_lshlrev_b32_e32 v82, 16, v51
	v_and_b32_e32 v83, 0xffff0000, v51
	s_waitcnt vmcnt(4)
	v_mov_b32_e32 v48, v160
	v_mov_b32_e32 v49, v161
	v_mov_b32_e32 v50, v162
	v_mov_b32_e32 v51, v163
	v_sub_f32_e32 v59, v81, v65
	v_sub_f32_e32 v58, v80, v64
	v_sub_f32_e32 v79, v79, v67
	v_sub_f32_e32 v78, v78, v66
	v_cndmask_b32_e64 v51, v51, 0, s[36:37]
	v_cndmask_b32_e64 v50, v50, 0, s[36:37]
	v_cndmask_b32_e64 v49, v49, 0, s[36:37]
	v_cndmask_b32_e64 v48, v48, 0, s[36:37]
	v_lshlrev_b32_e32 v84, 16, v48
	v_and_b32_e32 v85, 0xffff0000, v48
	v_lshlrev_b32_e32 v86, 16, v49
	v_and_b32_e32 v87, 0xffff0000, v49
	v_lshlrev_b32_e32 v88, 16, v50
	v_and_b32_e32 v89, 0xffff0000, v50
	v_lshlrev_b32_e32 v90, 16, v51
	v_and_b32_e32 v91, 0xffff0000, v51
	s_waitcnt vmcnt(3)
	v_mov_b32_e32 v48, v210
	v_mov_b32_e32 v49, v211
	v_mov_b32_e32 v50, v212
	v_mov_b32_e32 v51, v213
	s_waitcnt vmcnt(2)
	v_mov_b32_e32 v70, v232
	v_mov_b32_e32 v71, v233
	v_mov_b32_e32 v72, v234
	v_mov_b32_e32 v73, v235
	s_waitcnt vmcnt(1)
	v_mov_b32_e32 v52, v240
	v_mov_b32_e32 v53, v241
	v_mov_b32_e32 v54, v242
	v_mov_b32_e32 v55, v243
	s_waitcnt vmcnt(0)
	v_mov_b32_e32 v74, v244
	v_mov_b32_e32 v75, v245
	v_mov_b32_e32 v76, v246
	v_mov_b32_e32 v77, v247
	v_pk_fma_f32 v[70:71], v[70:71], v[78:79], v[66:67]
	v_pk_fma_f32 v[58:59], v[72:73], v[58:59], v[64:65]
	v_sub_f32_e32 v67, v85, v67
	v_sub_f32_e32 v66, v84, v66
	v_sub_f32_e32 v65, v87, v65
	v_sub_f32_e32 v64, v86, v64
	v_pk_fma_f32 v[58:59], v[76:77], v[64:65], v[58:59]
	v_pk_fma_f32 v[64:65], v[74:75], v[66:67], v[70:71]
	v_mul_f32_e32 v58, 0xbfb8aa3b, v58
	v_mul_f32_e32 v64, 0xbfb8aa3b, v64
	v_mul_f32_e32 v65, 0xbfb8aa3b, v65
	v_exp_f32_e32 v64, v64
	v_exp_f32_e32 v65, v65
	v_mul_f32_e32 v59, 0xbfb8aa3b, v59
	v_exp_f32_e32 v58, v58
	v_exp_f32_e32 v59, v59
	v_pk_add_f32 v[64:65], v[64:65], 1.0 op_sel_hi:[1,0]
	v_pk_add_f32 v[58:59], v[58:59], 1.0 op_sel_hi:[1,0]
	v_div_scale_f32 v66, s[4:5], v65, v65, 1.0
	v_rcp_f32_e32 v67, v66
	s_nop 0
	v_fma_f32 v70, -v66, v67, 1.0
	v_fmac_f32_e32 v67, v70, v67
	v_div_scale_f32 v70, vcc, 1.0, v65, 1.0
	v_mul_f32_e32 v71, v70, v67
	v_fma_f32 v72, -v66, v71, v70
	v_fmac_f32_e32 v71, v72, v67
	v_fma_f32 v66, -v66, v71, v70
	v_div_fmas_f32 v66, v66, v67, v71
	v_div_fixup_f32 v66, v66, v65, 1.0
	v_div_scale_f32 v65, s[4:5], v64, v64, 1.0
	v_rcp_f32_e32 v67, v65
	s_nop 0
	v_fma_f32 v70, -v65, v67, 1.0
	v_fmac_f32_e32 v67, v70, v67
	v_div_scale_f32 v70, vcc, 1.0, v64, 1.0
	v_mul_f32_e32 v71, v70, v67
	v_fma_f32 v72, -v65, v71, v70
	v_fmac_f32_e32 v71, v72, v67
	v_fma_f32 v65, -v65, v71, v70
	v_div_fmas_f32 v65, v65, v67, v71
	v_div_fixup_f32 v67, v65, v64, 1.0
	v_div_scale_f32 v64, s[4:5], v59, v59, 1.0
	v_rcp_f32_e32 v65, v64
	s_nop 0
	v_fma_f32 v70, -v64, v65, 1.0
	v_fmac_f32_e32 v65, v70, v65
	v_div_scale_f32 v70, vcc, 1.0, v59, 1.0
	v_mul_f32_e32 v71, v70, v65
	v_fma_f32 v72, -v64, v71, v70
	v_fmac_f32_e32 v71, v72, v65
	v_fma_f32 v64, -v64, v71, v70
	v_div_fmas_f32 v64, v64, v65, v71
	v_div_fixup_f32 v70, v64, v59, 1.0
	v_div_scale_f32 v59, s[4:5], v58, v58, 1.0
	v_rcp_f32_e32 v64, v59
	s_nop 0
	v_fma_f32 v65, -v59, v64, 1.0
	v_fmac_f32_e32 v64, v65, v64
	v_div_scale_f32 v65, vcc, 1.0, v58, 1.0
	v_mul_f32_e32 v71, v65, v64
	v_fma_f32 v72, -v59, v71, v65
	v_fmac_f32_e32 v71, v72, v64
	v_fma_f32 v59, -v59, v71, v65
	v_div_fmas_f32 v59, v59, v64, v71
	v_div_fixup_f32 v71, v59, v58, 1.0
	v_sub_f32_e32 v59, v83, v61
	v_sub_f32_e32 v58, v82, v60
	v_sub_f32_e32 v65, v69, v63
	v_sub_f32_e32 v64, v68, v62
	v_pk_fma_f32 v[48:49], v[48:49], v[64:65], v[62:63]
	v_pk_fma_f32 v[50:51], v[50:51], v[58:59], v[60:61]
	v_sub_f32_e32 v59, v89, v63
	v_sub_f32_e32 v58, v88, v62
	v_pk_fma_f32 v[48:49], v[52:53], v[58:59], v[48:49]
	v_sub_f32_e32 v61, v91, v61
	v_mul_f32_e32 v48, 0xbfb8aa3b, v48
	v_mul_f32_e32 v49, 0xbfb8aa3b, v49
	v_exp_f32_e32 v48, v48
	v_exp_f32_e32 v49, v49
	v_sub_f32_e32 v60, v90, v60
	v_pk_fma_f32 v[50:51], v[54:55], v[60:61], v[50:51]
	v_pk_add_f32 v[48:49], v[48:49], 1.0 op_sel_hi:[1,0]
	s_nop 0
	v_div_scale_f32 v52, s[4:5], v49, v49, 1.0
	v_rcp_f32_e32 v53, v52
	s_nop 0
	v_fma_f32 v54, -v52, v53, 1.0
	v_fmac_f32_e32 v53, v54, v53
	v_div_scale_f32 v54, vcc, 1.0, v49, 1.0
	v_mul_f32_e32 v55, v54, v53
	v_fma_f32 v58, -v52, v55, v54
	v_fmac_f32_e32 v55, v58, v53
	v_fma_f32 v52, -v52, v55, v54
	v_div_fmas_f32 v52, v52, v53, v55
	v_div_fixup_f32 v52, v52, v49, 1.0
	v_div_scale_f32 v49, s[4:5], v48, v48, 1.0
	v_rcp_f32_e32 v53, v49
	s_nop 0
	v_fma_f32 v54, -v49, v53, 1.0
	v_fmac_f32_e32 v53, v54, v53
	v_div_scale_f32 v54, vcc, 1.0, v48, 1.0
	v_mul_f32_e32 v55, v54, v53
	v_fma_f32 v58, -v49, v55, v54
	v_fmac_f32_e32 v55, v58, v53
	v_fma_f32 v49, -v49, v55, v54
	v_div_fmas_f32 v49, v49, v53, v55
	v_div_fixup_f32 v53, v49, v48, 1.0
	v_mul_f32_e32 v48, 0xbfb8aa3b, v50
	v_mul_f32_e32 v49, 0xbfb8aa3b, v51
	v_exp_f32_e32 v48, v48
	v_exp_f32_e32 v49, v49
	s_nop 0
	v_pk_add_f32 v[48:49], v[48:49], 1.0 op_sel_hi:[1,0]
	s_nop 0
	v_div_scale_f32 v50, s[4:5], v49, v49, 1.0
	v_rcp_f32_e32 v51, v50
	s_nop 0
	v_fma_f32 v54, -v50, v51, 1.0
	v_fmac_f32_e32 v51, v54, v51
	v_div_scale_f32 v54, vcc, 1.0, v49, 1.0
	v_mul_f32_e32 v55, v54, v51
	v_fma_f32 v58, -v50, v55, v54
	v_fmac_f32_e32 v55, v58, v51
	v_fma_f32 v50, -v50, v55, v54
	v_div_fmas_f32 v50, v50, v51, v55
	v_div_fixup_f32 v51, v50, v49, 1.0
	v_div_scale_f32 v49, s[4:5], v48, v48, 1.0
	v_rcp_f32_e32 v50, v49
	s_lshl_b32 s4, s10, 6
	s_or_b32 s6, s2, s4
	v_add_u32_e32 v190, s6, v164
	v_fma_f32 v54, -v49, v50, 1.0
	v_fmac_f32_e32 v50, v54, v50
	v_div_scale_f32 v54, vcc, 1.0, v48, 1.0
	v_mul_f32_e32 v55, v54, v50
	v_fma_f32 v58, -v49, v55, v54
	v_fmac_f32_e32 v55, v58, v50
	v_fma_f32 v49, -v49, v55, v54
	v_div_fmas_f32 v49, v49, v50, v55
	v_div_fixup_f32 v54, v49, v48, 1.0
	v_or_b32_e32 v58, s6, v227
	v_cvt_pk_bf16_f32 v48, v67, v66
	v_cvt_pk_bf16_f32 v49, v71, v70
	v_cvt_pk_bf16_f32 v50, v53, v52
	v_cvt_pk_bf16_f32 v51, v54, v51
	v_lshlrev_b32_e32 v208, 7, v58
	v_ashrrev_i32_e32 v191, 31, v190
	v_lshl_add_u64 v[54:55], v[168:169], 0, v[208:209]
	v_lshl_add_u64 v[52:53], v[190:191], 2, s[42:43]
	global_load_dwordx4 v[76:79], v[54:55], off
	global_load_dwordx4 v[80:83], v[54:55], off offset:64
	global_load_dwordx4 v[68:71], v[52:53], off offset:48
	global_load_dwordx4 v[72:75], v[52:53], off offset:32
	global_load_dwordx4 v[84:87], v[52:53], off offset:16
	global_load_dwordx4 v[96:99], v[52:53], off
	global_load_dwordx4 v[88:91], v[54:55], off offset:512
	global_load_dwordx4 v[92:95], v[54:55], off offset:576
	global_load_dwordx4 v[100:103], v[54:55], off offset:1024
	global_load_dwordx4 v[104:107], v[54:55], off offset:1088
	global_load_dwordx4 v[108:111], v[54:55], off offset:1536
	global_load_dwordx4 v[112:115], v[54:55], off offset:1600
	v_lshlrev_b64 v[52:53], 11, v[56:57]
	v_lshl_add_u64 v[192:193], s[52:53], 0, v[52:53]
	v_lshl_add_u64 v[52:53], v[178:179], 0, v[52:53]
	s_lshl_b32 s24, s6, 1
	v_lshl_add_u64 v[194:195], v[52:53], 0, s[24:25]
	v_or_b32_e32 v52, s6, v228
	v_lshl_add_u64 v[198:199], v[180:181], 0, v[208:209]
	v_lshlrev_b32_e32 v208, 7, v52
	v_lshl_add_u64 v[204:205], v[180:181], 0, v[208:209]
	v_mul_u32_u24_e32 v208, 0x140, v52
	v_or_b32_e32 v52, s6, v229
	v_lshl_add_u64 v[206:207], v[184:185], 0, v[208:209]
	v_mul_u32_u24_e32 v208, 0x140, v52
	v_or_b32_e32 v53, s6, v230
	v_lshl_add_u64 v[216:217], v[184:185], 0, v[208:209]
	v_lshlrev_b32_e32 v208, 7, v53
	v_lshl_add_u64 v[218:219], v[180:181], 0, v[208:209]
	v_mul_u32_u24_e32 v208, 0x140, v53
	v_add_lshl_u32 v196, s6, v165, 7
	s_movk_i32 s4, 0x140
	v_lshl_add_u64 v[220:221], v[184:185], 0, v[208:209]
	v_lshlrev_b32_e32 v208, 7, v52
	v_lshl_add_u64 v[200:201], v[182:183], 0, v[196:197]
	v_mad_u64_u32 v[202:203], s[4:5], v58, s4, v[184:185]
	v_lshl_add_u64 v[222:223], v[180:181], 0, v[208:209]
